# GEMM tile loops: next-tile index computation (integer division etc.) moved off the tile-start critical path into the first K-iteration's load segment (7 of 12 GEMM loops)
# baseline (speedup 1.0000x reference)
; #define PG8_STAGE(bufoff, gbase, voff) do { _Pragma("unroll") for (int _i = 0; _i < 2; ++_i) \
;         __builtin_amdgcn_global_load_lds((const unsigned*)((const char*)(gbase) + (voff)[_i]), (PG8_LAS unsigned*)(lds + (bufoff) + ldsw + _i * 8192), 16, 0, 0); } while (0)
; #define PG8_LDA(dst, b, h) do { _Pragma("unroll") for (int m = 0; m < 4; ++m) _Pragma("unroll") for (int k = 0; k < 2; ++k) dst[m][k] = *(const PG8_LAS bf16x8*)(lds + PG8_SA(b, h) + aoff + m * 2048 + k * 1024); } while (0)
; #define PG8_LDB(dst, b, h) do { _Pragma("unroll") for (int n = 0; n < 2; ++n) _Pragma("unroll") for (int k = 0; k < 2; ++k) dst[n][k] = *(const PG8_LAS bf16x8*)(lds + PG8_SB(b, h) + boff + n * 2048 + k * 1024); } while (0)
; #define PG8_SCHED __builtin_amdgcn_sched_barrier(0)
;     __host__ __device__ bool next(int i, Unit& u) const {
;         const long L = (long)i * G + c; if (L >= nwg) return false;
;         int wgid = (int)L; { const int q = nwg / NXCD, r = nwg % NXCD, xcd = wgid % NXCD, off = wgid / NXCD; wgid = (xcd < r ? xcd * (q + 1) : r * (q + 1) + (xcd - r) * q) + off; }
;         const int nig = WGM * nN, gid = wgid / nig, fm = gid * WGM, gsz = (nM - fm) < WGM ? (nM - fm) : WGM;
; template <class Epi, class Sched, bool ALIGN_EPI = false, bool SP2 = false, bool TA = true>
; __device__ __forceinline__ void gemm_phase(PG8_LAS unsigned char* lds, const Gemm g, const Sched& S, const Epi& E) {
;     ...
;         const bool has_next = S.next(ui + 1, nxt);
;         const char* nA = has_next ? (const char*)g.A + (size_t)nxt.pm * tstep : cA; const char* nB = has_next ? (const char*)g.Bt + (size_t)nxt.pn * tstep : cB;
; #pragma unroll 1
;         for (int t = 0; t < nt; t += 2) {
;             const bool last = (t == nt - 2);
;             const char* a1 = cA + (size_t)(t + 1) * kstep;
;             const char* a2 = last ? nA : cA + (size_t)(t + 2) * kstep; const char* b2 = last ? nB : cB + (size_t)(t + 2) * kstepB;
;             const char* a3 = a2 + kstep; const char* b3 = b2 + kstepB;
;             if (last && has_next) S.a_ready(nxt);
;             if constexpr (SP2) {
;             PG8_LDB(B0, 0, 0); PG8_LDB(B1, 0, 1); PG8_SCHED; PG8_LDA(At, 0, 0); PG8_STAGE(PG8_SA(1, 1), a1 + hstep, voffA);
.LBB0_686:
	s_add_u32 s0, s0, 0x44000
	s_addc_u32 s1, s1, 0
	s_add_u32 s76, s76, 0x8000
	s_addc_u32 s77, s77, 0
	s_mov_b32 s79, -2
	s_waitcnt lgkmcnt(0)
	s_waitcnt lgkmcnt(0)
	ds_read_b128 v[80:83], v179
	ds_read_b128 v[84:87], v179 offset:1024
	ds_read_b128 v[88:91], v179 offset:2048
	ds_read_b128 v[92:95], v179 offset:3072
	ds_read_b128 v[144:147], v180
	ds_read_b128 v[148:151], v180 offset:1024
	ds_read_b128 v[152:155], v180 offset:2048
	ds_read_b128 v[156:159], v180 offset:3072
	s_add_u32 s80, s0, 0xfffc4000
	s_addc_u32 s81, s1, -1
	s_cmp_eq_u32 s79, 12
	s_cselect_b32 s81, s61, s81
	s_cselect_b32 s80, s75, s80
	s_cselect_b32 s83, s59, s77
	s_cselect_b32 s82, s78, s76
	v_lshl_add_u64 v[210:211], s[0:1], 0, v[160:161]
	s_add_i32 m0, s30, 0xc000
	ds_read_b128 v[168:171], v181
	ds_read_b128 v[172:175], v181 offset:1024
	ds_read_b128 v[184:187], v181 offset:2048
	ds_read_b128 v[188:191], v181 offset:3072
	ds_read_b128 v[192:195], v181 offset:4096
	ds_read_b128 v[196:199], v181 offset:5120
	ds_read_b128 v[200:203], v181 offset:6144
	ds_read_b128 v[204:207], v181 offset:7168
	global_load_lds_dwordx4 v[210:211], off
	v_lshl_add_u64 v[210:211], v[210:211], 0, s[8:9]
	s_add_i32 m0, s30, 0xe000
	s_nop 0
	global_load_lds_dwordx4 v[210:211], off
	s_add_i32 s89, s89, 1
	s_mul_i32 s4, s89, s84
	s_mul_hi_u32 s5, s89, s85
	s_add_i32 s5, s5, s4
	s_mul_i32 s4, s89, s85
	s_add_u32 s70, s4, s20
	s_addc_u32 s71, s5, s86
	v_cmp_gt_i64_e32 vcc, s[70:71], v[166:167]
	v_cmp_lt_i64_e64 s[4:5], s[70:71], v[164:165]
	s_cbranch_vccnz .LBB0_692
	s_ashr_i32 s58, s70, 31
	s_lshr_b32 s58, s58, 29
	s_add_i32 s60, s70, s58
	s_and_b32 s58, s60, -8
	s_sub_i32 s61, s70, s58
	s_cmp_gt_i32 s61, -1
	s_mov_b64 s[58:59], -1
	s_cbranch_scc0 .LBB0_689
	s_lshl_b32 s70, s61, 6
	s_mov_b64 s[58:59], 0

; #define PG8_STAGE(bufoff, gbase, voff) do { _Pragma("unroll") for (int _i = 0; _i < 2; ++_i) \
;         __builtin_amdgcn_global_load_lds((const unsigned*)((const char*)(gbase) + (voff)[_i]), (PG8_LAS unsigned*)(lds + (bufoff) + ldsw + _i * 8192), 16, 0, 0); } while (0)
; #define PG8_LDA(dst, b, h) do { _Pragma("unroll") for (int m = 0; m < 4; ++m) _Pragma("unroll") for (int k = 0; k < 2; ++k) dst[m][k] = *(const PG8_LAS bf16x8*)(lds + PG8_SA(b, h) + aoff + m * 2048 + k * 1024); } while (0)
; #define PG8_LDB(dst, b, h) do { _Pragma("unroll") for (int n = 0; n < 2; ++n) _Pragma("unroll") for (int k = 0; k < 2; ++k) dst[n][k] = *(const PG8_LAS bf16x8*)(lds + PG8_SB(b, h) + boff + n * 2048 + k * 1024); } while (0)
; #define PG8_WAIT_V(n) asm volatile("s_waitcnt vmcnt(" #n ")" ::: "memory")
; #define PG8_WAIT_L(n) asm volatile("s_waitcnt lgkmcnt(" #n ")" ::: "memory")
; #define PG8_BAR __builtin_amdgcn_s_barrier()
; #define PG8_SCHED __builtin_amdgcn_sched_barrier(0)
; template <class Epi, class Sched, bool ALIGN_EPI = false, bool SP2 = false, bool TA = true>
; __device__ __forceinline__ void gemm_phase(PG8_LAS unsigned char* lds, const Gemm g, const Sched& S, const Epi& E) {
;     ...
;         const char* nA = has_next ? (const char*)g.A + (size_t)nxt.pm * tstep : cA; const char* nB = has_next ? (const char*)g.Bt + (size_t)nxt.pn * tstep : cB;
; #pragma unroll 1
;         for (int t = 0; t < nt; t += 2) {
;             const bool last = (t == nt - 2);
;             const char* a1 = cA + (size_t)(t + 1) * kstep;
;             const char* a2 = last ? nA : cA + (size_t)(t + 2) * kstep; const char* b2 = last ? nB : cB + (size_t)(t + 2) * kstepB;
;             const char* a3 = a2 + kstep; const char* b3 = b2 + kstepB;
;             if (last && has_next) S.a_ready(nxt);
;             if constexpr (SP2) {
;             PG8_LDB(B0, 0, 0); PG8_LDB(B1, 0, 1); PG8_SCHED; PG8_LDA(At, 0, 0); PG8_STAGE(PG8_SA(1, 1), a1 + hstep, voffA);
;             PG8_WAIT_V(8); PG8_WAIT_L(0); PG8_BAR; PG8_MMA(0, 0, At, B0); PG8_MMA(0, 1, At, B1); PG8_BAR; PG8_SCHED;
;             PG8_LDA(At, 0, 1); PG8_STAGE(PG8_SB(0, 0), b2, voffB); PG8_STAGE(PG8_SB(0, 1), b2 + hstep, voffB); PG8_STAGE(PG8_SA(0, 0), a2, voffA);
;             PG8_WAIT_V(8); PG8_WAIT_L(0); PG8_BAR; PG8_MMA(1, 0, At, B0); PG8_MMA(1, 1, At, B1); PG8_BAR; PG8_SCHED;
.LBB0_692:
	s_ashr_i32 s95, s94, 31
	s_lshl_b64 s[70:71], s[94:95], 19
	s_add_u32 s26, s18, s70
	s_addc_u32 s27, s19, s71
	s_and_b64 s[72:73], s[4:5], exec
	s_cselect_b32 s61, s27, s1
	s_cselect_b32 s75, s26, s0
	s_ashr_i32 s97, s96, 31
	s_lshl_b64 s[72:73], s[96:97], 19
	s_add_u32 s92, s21, s72
	s_addc_u32 s93, s22, s73
	s_and_b64 s[98:99], s[4:5], exec
	s_cselect_b32 s59, s93, s77
	s_cselect_b32 s78, s92, s76
	s_waitcnt vmcnt(8)
	s_waitcnt lgkmcnt(0)
	s_barrier
	s_setprio 1
	s_waitcnt lgkmcnt(0)
	v_mfma_f32_16x16x32_bf16 v[140:143], v[80:83], v[168:171], 0
	v_mfma_f32_16x16x32_bf16 v[136:139], v[88:91], v[168:171], 0
	v_mfma_f32_16x16x32_bf16 v[124:127], v[80:83], v[184:187], 0
	v_mfma_f32_16x16x32_bf16 v[120:123], v[88:91], v[184:187], 0
	v_mfma_f32_16x16x32_bf16 v[108:111], v[80:83], v[192:195], 0
	v_mfma_f32_16x16x32_bf16 v[104:107], v[88:91], v[192:195], 0
	v_mfma_f32_16x16x32_bf16 v[76:79], v[80:83], v[200:203], 0
	v_mfma_f32_16x16x32_bf16 v[72:75], v[88:91], v[200:203], 0
	v_mfma_f32_16x16x32_bf16 v[140:143], v[84:87], v[172:175], v[140:143]
	v_mfma_f32_16x16x32_bf16 v[136:139], v[92:95], v[172:175], v[136:139]
	v_mfma_f32_16x16x32_bf16 v[124:127], v[84:87], v[188:191], v[124:127]
	v_mfma_f32_16x16x32_bf16 v[120:123], v[92:95], v[188:191], v[120:123]
	v_mfma_f32_16x16x32_bf16 v[108:111], v[84:87], v[196:199], v[108:111]
	v_mfma_f32_16x16x32_bf16 v[104:107], v[92:95], v[196:199], v[104:107]
	v_mfma_f32_16x16x32_bf16 v[76:79], v[84:87], v[204:207], v[76:79]
	v_mfma_f32_16x16x32_bf16 v[72:75], v[92:95], v[204:207], v[72:75]
	s_setprio 0
	s_setprio 1
	v_mfma_f32_16x16x32_bf16 v[132:135], v[144:147], v[168:171], 0
	v_mfma_f32_16x16x32_bf16 v[128:131], v[152:155], v[168:171], 0
	v_mfma_f32_16x16x32_bf16 v[116:119], v[144:147], v[184:187], 0
	v_mfma_f32_16x16x32_bf16 v[112:115], v[152:155], v[184:187], 0
	v_mfma_f32_16x16x32_bf16 v[100:103], v[144:147], v[192:195], 0
	v_mfma_f32_16x16x32_bf16 v[96:99], v[152:155], v[192:195], 0
	v_mfma_f32_16x16x32_bf16 v[68:71], v[144:147], v[200:203], 0
	v_mfma_f32_16x16x32_bf16 v[64:67], v[152:155], v[200:203], 0
	v_mfma_f32_16x16x32_bf16 v[132:135], v[148:151], v[172:175], v[132:135]
	v_mfma_f32_16x16x32_bf16 v[128:131], v[156:159], v[172:175], v[128:131]
	v_mfma_f32_16x16x32_bf16 v[116:119], v[148:151], v[188:191], v[116:119]
	v_mfma_f32_16x16x32_bf16 v[112:115], v[156:159], v[188:191], v[112:115]
	v_mfma_f32_16x16x32_bf16 v[100:103], v[148:151], v[196:199], v[100:103]
	v_mfma_f32_16x16x32_bf16 v[96:99], v[156:159], v[196:199], v[96:99]
	v_mfma_f32_16x16x32_bf16 v[68:71], v[148:151], v[204:207], v[68:71]
	v_mfma_f32_16x16x32_bf16 v[64:67], v[156:159], v[204:207], v[64:67]
	s_setprio 0
	s_barrier
	v_lshl_add_u64 v[210:211], s[82:83], 0, v[160:161]
	s_add_i32 s82, s87, s23
	s_mov_b32 m0, s82
	ds_read_b128 v[168:171], v181 offset:16384
	ds_read_b128 v[172:175], v181 offset:17408
	ds_read_b128 v[184:187], v181 offset:18432
	ds_read_b128 v[188:191], v181 offset:19456
	ds_read_b128 v[192:195], v181 offset:20480
	ds_read_b128 v[196:199], v181 offset:21504
	ds_read_b128 v[200:203], v181 offset:22528
	ds_read_b128 v[204:207], v181 offset:23552
	global_load_lds_dwordx4 v[210:211], off
	v_lshl_add_u64 v[212:213], v[210:211], 0, s[8:9]
	s_add_i32 m0, s82, 0x2000
	s_add_i32 s82, s88, s23
	global_load_lds_dwordx4 v[212:213], off
	v_lshl_add_u64 v[212:213], v[210:211], 0, s[10:11]
	s_mov_b32 m0, s82
	s_nop 0
	global_load_lds_dwordx4 v[212:213], off
	v_lshl_add_u64 v[212:213], v[210:211], 0, s[12:13]
	s_add_i32 m0, s82, 0x2000
	s_nop 0
	global_load_lds_dwordx4 v[212:213], off
	v_lshl_add_u64 v[212:213], s[80:81], 0, v[160:161]
	s_mov_b32 m0, s30
	v_lshl_add_u64 v[214:215], v[212:213], 0, s[8:9]
	global_load_lds_dwordx4 v[212:213], off
	s_mov_b32 m0, s31
	s_nop 0
	global_load_lds_dwordx4 v[214:215], off
	s_waitcnt vmcnt(8)
	s_waitcnt lgkmcnt(0)
	s_barrier
	s_setprio 1
	s_waitcnt lgkmcnt(0)
	v_mfma_f32_16x16x32_bf16 v[60:63], v[80:83], v[168:171], 0
	v_mfma_f32_16x16x32_bf16 v[56:59], v[88:91], v[168:171], 0
	v_mfma_f32_16x16x32_bf16 v[44:47], v[80:83], v[184:187], 0
	v_mfma_f32_16x16x32_bf16 v[40:43], v[88:91], v[184:187], 0
	v_mfma_f32_16x16x32_bf16 v[28:31], v[80:83], v[192:195], 0
	v_mfma_f32_16x16x32_bf16 v[24:27], v[88:91], v[192:195], 0
	v_mfma_f32_16x16x32_bf16 v[12:15], v[80:83], v[200:203], 0
	v_mfma_f32_16x16x32_bf16 v[8:11], v[88:91], v[200:203], 0
	v_mfma_f32_16x16x32_bf16 v[60:63], v[84:87], v[172:175], v[60:63]
	v_mfma_f32_16x16x32_bf16 v[56:59], v[92:95], v[172:175], v[56:59]
	v_mfma_f32_16x16x32_bf16 v[44:47], v[84:87], v[188:191], v[44:47]
	v_mfma_f32_16x16x32_bf16 v[40:43], v[92:95], v[188:191], v[40:43]
	v_mfma_f32_16x16x32_bf16 v[28:31], v[84:87], v[196:199], v[28:31]
	v_mfma_f32_16x16x32_bf16 v[24:27], v[92:95], v[196:199], v[24:27]
	v_mfma_f32_16x16x32_bf16 v[12:15], v[84:87], v[204:207], v[12:15]
	v_mfma_f32_16x16x32_bf16 v[8:11], v[92:95], v[204:207], v[8:11]
	s_setprio 0
	s_setprio 1
	v_mfma_f32_16x16x32_bf16 v[52:55], v[144:147], v[168:171], 0
	v_mfma_f32_16x16x32_bf16 v[48:51], v[152:155], v[168:171], 0
	v_mfma_f32_16x16x32_bf16 v[36:39], v[144:147], v[184:187], 0
	v_mfma_f32_16x16x32_bf16 v[32:35], v[152:155], v[184:187], 0
	v_mfma_f32_16x16x32_bf16 v[20:23], v[144:147], v[192:195], 0
	v_mfma_f32_16x16x32_bf16 v[16:19], v[152:155], v[192:195], 0
	v_mfma_f32_16x16x32_bf16 v[4:7], v[144:147], v[200:203], 0
	v_mfma_f32_16x16x32_bf16 v[0:3], v[152:155], v[200:203], 0
	v_mfma_f32_16x16x32_bf16 v[52:55], v[148:151], v[172:175], v[52:55]
	v_mfma_f32_16x16x32_bf16 v[48:51], v[156:159], v[172:175], v[48:51]
	v_mfma_f32_16x16x32_bf16 v[36:39], v[148:151], v[188:191], v[36:39]
	v_mfma_f32_16x16x32_bf16 v[32:35], v[156:159], v[188:191], v[32:35]
	v_mfma_f32_16x16x32_bf16 v[20:23], v[148:151], v[196:199], v[20:23]
	v_mfma_f32_16x16x32_bf16 v[16:19], v[156:159], v[196:199], v[16:19]
	v_mfma_f32_16x16x32_bf16 v[4:7], v[148:151], v[204:207], v[4:7]
	v_mfma_f32_16x16x32_bf16 v[0:3], v[156:159], v[204:207], v[0:3]
	s_setprio 0
	s_barrier
; #define PG8_STAGE(bufoff, gbase, voff) do { _Pragma("unroll") for (int _i = 0; _i < 2; ++_i) \
;         __builtin_amdgcn_global_load_lds((const unsigned*)((const char*)(gbase) + (voff)[_i]), (PG8_LAS unsigned*)(lds + (bufoff) + ldsw + _i * 8192), 16, 0, 0); } while (0)
; #define PG8_LDA(dst, b, h) do { _Pragma("unroll") for (int m = 0; m < 4; ++m) _Pragma("unroll") for (int k = 0; k < 2; ++k) dst[m][k] = *(const PG8_LAS bf16x8*)(lds + PG8_SA(b, h) + aoff + m * 2048 + k * 1024); } while (0)
; #define PG8_LDB(dst, b, h) do { _Pragma("unroll") for (int n = 0; n < 2; ++n) _Pragma("unroll") for (int k = 0; k < 2; ++k) dst[n][k] = *(const PG8_LAS bf16x8*)(lds + PG8_SB(b, h) + boff + n * 2048 + k * 1024); } while (0)
; #define PG8_MMA(ai, bj, At, Bt) do { __builtin_amdgcn_s_setprio(1); _Pragma("unroll") for (int m = 0; m < 4; ++m) _Pragma("unroll") for (int n = 0; n < 2; ++n) _Pragma("unroll") for (int k = 0; k < 2; ++k) \
;         acc[ai][bj][m][n] = __builtin_amdgcn_mfma_f32_16x16x32_bf16(Bt[n][k], At[m][k], acc[ai][bj][m][n], 0, 0, 0); __builtin_amdgcn_s_setprio(0); } while (0)
; #define PG8_WAIT_V(n) asm volatile("s_waitcnt vmcnt(" #n ")" ::: "memory")
; #define PG8_WAIT_L(n) asm volatile("s_waitcnt lgkmcnt(" #n ")" ::: "memory")
; #define PG8_BAR __builtin_amdgcn_s_barrier()
; #define PG8_SCHED __builtin_amdgcn_sched_barrier(0)
; template <class Epi, class Sched, bool ALIGN_EPI = false, bool SP2 = false, bool TA = true>
; __device__ __forceinline__ void gemm_phase(PG8_LAS unsigned char* lds, const Gemm g, const Sched& S, const Epi& E) {
;     ...
;             PG8_LDB(B0, 1, 0); PG8_LDB(B1, 1, 1); PG8_SCHED; PG8_LDA(At, 1, 0); PG8_STAGE(PG8_SA(0, 1), a2 + hstep, voffA);
;             PG8_WAIT_V(8); PG8_WAIT_L(0); PG8_BAR; PG8_MMA(0, 0, At, B0); PG8_MMA(0, 1, At, B1); PG8_BAR; PG8_SCHED;
;             PG8_LDA(At, 1, 1); PG8_STAGE(PG8_SB(1, 0), b3, voffB); PG8_STAGE(PG8_SB(1, 1), b3 + hstep, voffB); PG8_STAGE(PG8_SA(1, 0), a3, voffA);
;             PG8_WAIT_V(8); PG8_WAIT_L(0); PG8_BAR; PG8_MMA(1, 0, At, B0); PG8_MMA(1, 1, At, B1); PG8_BAR; PG8_SCHED;
	s_add_i32 s80, 0, 0x18000
	s_add_i32 s81, 0, 0x1c000
	v_add_u32_e32 v92, s80, v178
	v_add_u32_e32 v156, s81, v178
	ds_read_b128 v[80:83], v92
	ds_read_b128 v[84:87], v92 offset:1024
	ds_read_b128 v[88:91], v92 offset:2048
	ds_read_b128 v[92:95], v92 offset:3072
	ds_read_b128 v[144:147], v156
	ds_read_b128 v[148:151], v156 offset:1024
	ds_read_b128 v[152:155], v156 offset:2048
	ds_read_b128 v[156:159], v156 offset:3072
	s_mov_b32 m0, s33
	v_lshl_add_u64 v[214:215], v[212:213], 0, s[10:11]
	ds_read_b128 v[168:171], v181 offset:32768
	ds_read_b128 v[172:175], v181 offset:33792
	ds_read_b128 v[184:187], v181 offset:34816
	ds_read_b128 v[188:191], v181 offset:35840
	ds_read_b128 v[192:195], v181 offset:36864
	ds_read_b128 v[196:199], v181 offset:37888
	ds_read_b128 v[200:203], v181 offset:38912
	ds_read_b128 v[204:207], v181 offset:39936
	global_load_lds_dwordx4 v[214:215], off
	v_lshl_add_u64 v[214:215], v[212:213], 0, s[12:13]
	s_mov_b32 m0, s36
	s_nop 0
	global_load_lds_dwordx4 v[214:215], off
	s_waitcnt vmcnt(8)
	s_waitcnt lgkmcnt(0)
	s_barrier
	s_setprio 1
	s_waitcnt lgkmcnt(0)
	v_mfma_f32_16x16x32_bf16 v[140:143], v[80:83], v[168:171], v[140:143]
	v_mfma_f32_16x16x32_bf16 v[136:139], v[88:91], v[168:171], v[136:139]
	v_mfma_f32_16x16x32_bf16 v[124:127], v[80:83], v[184:187], v[124:127]
	v_mfma_f32_16x16x32_bf16 v[120:123], v[88:91], v[184:187], v[120:123]
	v_mfma_f32_16x16x32_bf16 v[108:111], v[80:83], v[192:195], v[108:111]
	v_mfma_f32_16x16x32_bf16 v[104:107], v[88:91], v[192:195], v[104:107]
	v_mfma_f32_16x16x32_bf16 v[76:79], v[80:83], v[200:203], v[76:79]
	v_mfma_f32_16x16x32_bf16 v[72:75], v[88:91], v[200:203], v[72:75]
	v_mfma_f32_16x16x32_bf16 v[140:143], v[84:87], v[172:175], v[140:143]
	v_mfma_f32_16x16x32_bf16 v[136:139], v[92:95], v[172:175], v[136:139]
	v_mfma_f32_16x16x32_bf16 v[124:127], v[84:87], v[188:191], v[124:127]
	v_mfma_f32_16x16x32_bf16 v[120:123], v[92:95], v[188:191], v[120:123]
	v_mfma_f32_16x16x32_bf16 v[108:111], v[84:87], v[196:199], v[108:111]
	v_mfma_f32_16x16x32_bf16 v[104:107], v[92:95], v[196:199], v[104:107]
	v_mfma_f32_16x16x32_bf16 v[76:79], v[84:87], v[204:207], v[76:79]
	v_mfma_f32_16x16x32_bf16 v[72:75], v[92:95], v[204:207], v[72:75]
	s_setprio 0
	s_setprio 1
	v_mfma_f32_16x16x32_bf16 v[132:135], v[144:147], v[168:171], v[132:135]
	v_mfma_f32_16x16x32_bf16 v[128:131], v[152:155], v[168:171], v[128:131]
	v_mfma_f32_16x16x32_bf16 v[116:119], v[144:147], v[184:187], v[116:119]
	v_mfma_f32_16x16x32_bf16 v[112:115], v[152:155], v[184:187], v[112:115]
	v_mfma_f32_16x16x32_bf16 v[100:103], v[144:147], v[192:195], v[100:103]
	v_mfma_f32_16x16x32_bf16 v[96:99], v[152:155], v[192:195], v[96:99]
	v_mfma_f32_16x16x32_bf16 v[68:71], v[144:147], v[200:203], v[68:71]
	v_mfma_f32_16x16x32_bf16 v[64:67], v[152:155], v[200:203], v[64:67]
	v_mfma_f32_16x16x32_bf16 v[132:135], v[148:151], v[172:175], v[132:135]
	v_mfma_f32_16x16x32_bf16 v[128:131], v[156:159], v[172:175], v[128:131]
	v_mfma_f32_16x16x32_bf16 v[116:119], v[148:151], v[188:191], v[116:119]
	v_mfma_f32_16x16x32_bf16 v[112:115], v[156:159], v[188:191], v[112:115]
	v_mfma_f32_16x16x32_bf16 v[100:103], v[148:151], v[196:199], v[100:103]
	v_mfma_f32_16x16x32_bf16 v[96:99], v[156:159], v[196:199], v[96:99]
	v_mfma_f32_16x16x32_bf16 v[68:71], v[148:151], v[204:207], v[68:71]
	v_mfma_f32_16x16x32_bf16 v[64:67], v[156:159], v[204:207], v[64:67]
	s_setprio 0
	s_barrier
	s_add_i32 s80, s80, s23
	v_lshl_add_u64 v[214:215], v[210:211], 0, s[44:45]
	s_mov_b32 m0, s80
	ds_read_b128 v[168:171], v181 offset:49152
	ds_read_b128 v[172:175], v181 offset:50176
	ds_read_b128 v[184:187], v181 offset:51200
	ds_read_b128 v[188:191], v181 offset:52224
	ds_read_b128 v[192:195], v181 offset:53248
	ds_read_b128 v[196:199], v181 offset:54272
	ds_read_b128 v[200:203], v181 offset:55296
	ds_read_b128 v[204:207], v181 offset:56320
	global_load_lds_dwordx4 v[214:215], off
	v_lshl_add_u64 v[214:215], v[210:211], 0, s[46:47]
	s_add_i32 m0, s80, 0x2000
	s_add_i32 s80, s81, s23
	global_load_lds_dwordx4 v[214:215], off
	v_lshl_add_u64 v[214:215], v[210:211], 0, s[48:49]
	s_mov_b32 m0, s80
	v_lshl_add_u64 v[210:211], v[210:211], 0, s[50:51]
	global_load_lds_dwordx4 v[214:215], off
	s_add_i32 m0, s80, 0x2000
	s_nop 0
	global_load_lds_dwordx4 v[210:211], off
	v_lshl_add_u64 v[210:211], v[212:213], 0, s[44:45]
	s_mov_b32 m0, s37
	s_nop 0
	global_load_lds_dwordx4 v[210:211], off
	v_lshl_add_u64 v[210:211], v[212:213], 0, s[46:47]
	s_mov_b32 m0, s38
	s_nop 0
	global_load_lds_dwordx4 v[210:211], off
	s_waitcnt vmcnt(8)
	s_waitcnt lgkmcnt(0)
	s_barrier
	s_setprio 1
	s_waitcnt lgkmcnt(0)
	v_mfma_f32_16x16x32_bf16 v[60:63], v[80:83], v[168:171], v[60:63]
	v_mfma_f32_16x16x32_bf16 v[56:59], v[88:91], v[168:171], v[56:59]
	v_mfma_f32_16x16x32_bf16 v[44:47], v[80:83], v[184:187], v[44:47]
	v_mfma_f32_16x16x32_bf16 v[40:43], v[88:91], v[184:187], v[40:43]
	v_mfma_f32_16x16x32_bf16 v[28:31], v[80:83], v[192:195], v[28:31]
	v_mfma_f32_16x16x32_bf16 v[24:27], v[88:91], v[192:195], v[24:27]
	v_mfma_f32_16x16x32_bf16 v[12:15], v[80:83], v[200:203], v[12:15]
	v_mfma_f32_16x16x32_bf16 v[8:11], v[88:91], v[200:203], v[8:11]
	v_mfma_f32_16x16x32_bf16 v[60:63], v[84:87], v[172:175], v[60:63]
	v_mfma_f32_16x16x32_bf16 v[56:59], v[92:95], v[172:175], v[56:59]
	v_mfma_f32_16x16x32_bf16 v[44:47], v[84:87], v[188:191], v[44:47]
	v_mfma_f32_16x16x32_bf16 v[40:43], v[92:95], v[188:191], v[40:43]
	v_mfma_f32_16x16x32_bf16 v[28:31], v[84:87], v[196:199], v[28:31]
	v_mfma_f32_16x16x32_bf16 v[24:27], v[92:95], v[196:199], v[24:27]
	v_mfma_f32_16x16x32_bf16 v[12:15], v[84:87], v[204:207], v[12:15]
	v_mfma_f32_16x16x32_bf16 v[8:11], v[92:95], v[204:207], v[8:11]
	s_setprio 0
	s_setprio 1
	v_mfma_f32_16x16x32_bf16 v[52:55], v[144:147], v[168:171], v[52:55]
	v_mfma_f32_16x16x32_bf16 v[48:51], v[152:155], v[168:171], v[48:51]
	v_mfma_f32_16x16x32_bf16 v[36:39], v[144:147], v[184:187], v[36:39]
	v_mfma_f32_16x16x32_bf16 v[32:35], v[152:155], v[184:187], v[32:35]
	v_mfma_f32_16x16x32_bf16 v[20:23], v[144:147], v[192:195], v[20:23]
	v_mfma_f32_16x16x32_bf16 v[16:19], v[152:155], v[192:195], v[16:19]
	v_mfma_f32_16x16x32_bf16 v[4:7], v[144:147], v[200:203], v[4:7]
	v_mfma_f32_16x16x32_bf16 v[0:3], v[152:155], v[200:203], v[0:3]
	v_mfma_f32_16x16x32_bf16 v[52:55], v[148:151], v[172:175], v[52:55]
	v_mfma_f32_16x16x32_bf16 v[48:51], v[156:159], v[172:175], v[48:51]
	v_mfma_f32_16x16x32_bf16 v[36:39], v[148:151], v[188:191], v[36:39]
	v_mfma_f32_16x16x32_bf16 v[32:35], v[156:159], v[188:191], v[32:35]
	v_mfma_f32_16x16x32_bf16 v[20:23], v[148:151], v[196:199], v[20:23]
	v_mfma_f32_16x16x32_bf16 v[16:19], v[156:159], v[196:199], v[16:19]
	v_mfma_f32_16x16x32_bf16 v[4:7], v[148:151], v[204:207], v[4:7]
	v_mfma_f32_16x16x32_bf16 v[0:3], v[156:159], v[204:207], v[0:3]
	s_setprio 0
	s_barrier
	s_add_i32 s79, s79, 2
	s_add_u32 s0, s0, 0x8000
	s_addc_u32 s1, s1, 0
	s_add_u32 s76, s76, 0x8000
	s_addc_u32 s77, s77, 0
	s_cmp_gt_u32 s79, 13

; #define PG8_STAGE(bufoff, gbase, voff) do { _Pragma("unroll") for (int _i = 0; _i < 2; ++_i) \
;         __builtin_amdgcn_global_load_lds((const unsigned*)((const char*)(gbase) + (voff)[_i]), (PG8_LAS unsigned*)(lds + (bufoff) + ldsw + _i * 8192), 16, 0, 0); } while (0)
; #define PG8_LDA(dst, b, h) do { _Pragma("unroll") for (int m = 0; m < 4; ++m) _Pragma("unroll") for (int k = 0; k < 2; ++k) dst[m][k] = *(const PG8_LAS bf16x8*)(lds + PG8_SA(b, h) + aoff + m * 2048 + k * 1024); } while (0)
; #define PG8_LDB(dst, b, h) do { _Pragma("unroll") for (int n = 0; n < 2; ++n) _Pragma("unroll") for (int k = 0; k < 2; ++k) dst[n][k] = *(const PG8_LAS bf16x8*)(lds + PG8_SB(b, h) + boff + n * 2048 + k * 1024); } while (0)
; #define PG8_SCHED __builtin_amdgcn_sched_barrier(0)
;     __host__ __device__ bool next(int i, Unit& u) const {
;         const long L = (long)i * G + c; if (L >= nwg) return false;
;         int wgid = (int)L; { const int q = nwg / NXCD, r = nwg % NXCD, xcd = wgid % NXCD, off = wgid / NXCD; wgid = (xcd < r ? xcd * (q + 1) : r * (q + 1) + (xcd - r) * q) + off; }
;         const int nig = WGM * nN, gid = wgid / nig, fm = gid * WGM, gsz = (nM - fm) < WGM ? (nM - fm) : WGM;
; template <class Epi, class Sched, bool ALIGN_EPI = false, bool SP2 = false, bool TA = true>
; __device__ __forceinline__ void gemm_phase(PG8_LAS unsigned char* lds, const Gemm g, const Sched& S, const Epi& E) {
;     ...
;         const bool has_next = S.next(ui + 1, nxt);
;         const char* nA = has_next ? (const char*)g.A + (size_t)nxt.pm * tstep : cA; const char* nB = has_next ? (const char*)g.Bt + (size_t)nxt.pn * tstep : cB;
; #pragma unroll 1
;         for (int t = 0; t < nt; t += 2) {
;             const bool last = (t == nt - 2);
;             const char* a1 = cA + (size_t)(t + 1) * kstep;
;             const char* a2 = last ? nA : cA + (size_t)(t + 2) * kstep; const char* b2 = last ? nB : cB + (size_t)(t + 2) * kstepB;
;             const char* a3 = a2 + kstep; const char* b3 = b2 + kstepB;
;             if (last && has_next) S.a_ready(nxt);
;             if constexpr (SP2) {
;             PG8_LDB(B0, 0, 0); PG8_LDB(B1, 0, 1); PG8_SCHED; PG8_LDA(At, 0, 0); PG8_STAGE(PG8_SA(1, 1), a1 + hstep, voffA);
.LBB0_993:
	s_add_u32 s76, s76, 0x44000
	s_addc_u32 s77, s77, 0
	s_add_u32 s78, s78, 0x8000
	s_addc_u32 s79, s79, 0
	s_mov_b32 s81, -2
	s_waitcnt lgkmcnt(0)
	ds_read_b128 v[128:131], v163
	ds_read_b128 v[132:135], v163 offset:1024
	ds_read_b128 v[136:139], v163 offset:2048
	ds_read_b128 v[140:143], v163 offset:3072
	ds_read_b128 v[152:155], v164
	ds_read_b128 v[168:171], v164 offset:1024
	ds_read_b128 v[172:175], v164 offset:2048
	ds_read_b128 v[176:179], v164 offset:3072
	s_add_u32 s82, s76, 0xfffc4000
	s_addc_u32 s83, s77, -1
	s_cmp_eq_u32 s81, 12
	s_cselect_b32 s83, s69, s83
	s_cselect_b32 s82, s75, s82
	s_cselect_b32 s85, s61, s79
	s_cselect_b32 s84, s80, s78
	v_lshl_add_u64 v[156:157], s[76:77], 0, v[144:145]
	s_add_i32 m0, s95, 0xc000
	ds_read_b128 v[180:183], v165
	ds_read_b128 v[184:187], v165 offset:1024
	ds_read_b128 v[188:191], v165 offset:2048
	ds_read_b128 v[192:195], v165 offset:3072
	ds_read_b128 v[196:199], v165 offset:4096
	ds_read_b128 v[200:203], v165 offset:5120
	ds_read_b128 v[204:207], v165 offset:6144
	ds_read_b128 v[210:213], v165 offset:7168
	global_load_lds_dwordx4 v[156:157], off
	v_lshl_add_u64 v[156:157], v[156:157], 0, s[12:13]
	s_add_i32 m0, s95, 0xe000
	s_nop 0
	global_load_lds_dwordx4 v[156:157], off
	s_add_i32 s22, s23, 1
	s_mul_i32 s6, s22, s39
	s_mul_hi_u32 s7, s22, s40
	s_add_i32 s7, s7, s6
	s_mul_i32 s6, s22, s40
	s_add_u32 s70, s6, s20
	s_addc_u32 s71, s7, s41
	v_cmp_gt_i64_e32 vcc, s[70:71], v[150:151]
	v_cmp_lt_i64_e64 s[6:7], s[70:71], v[148:149]
	s_cbranch_vccnz .LBB0_999
	s_ashr_i32 s60, s70, 31
	s_lshr_b32 s60, s60, 29
	s_add_i32 s68, s70, s60
	s_and_b32 s60, s68, -8
	s_sub_i32 s69, s70, s60
	s_cmp_gt_i32 s69, -1
	s_mov_b64 s[60:61], -1
	s_cbranch_scc0 .LBB0_996
	s_lshl_b32 s70, s69, 6
	s_mov_b64 s[60:61], 0

; #define PG8_STAGE(bufoff, gbase, voff) do { _Pragma("unroll") for (int _i = 0; _i < 2; ++_i) \
;         __builtin_amdgcn_global_load_lds((const unsigned*)((const char*)(gbase) + (voff)[_i]), (PG8_LAS unsigned*)(lds + (bufoff) + ldsw + _i * 8192), 16, 0, 0); } while (0)
; #define PG8_LDA(dst, b, h) do { _Pragma("unroll") for (int m = 0; m < 4; ++m) _Pragma("unroll") for (int k = 0; k < 2; ++k) dst[m][k] = *(const PG8_LAS bf16x8*)(lds + PG8_SA(b, h) + aoff + m * 2048 + k * 1024); } while (0)
; #define PG8_LDB(dst, b, h) do { _Pragma("unroll") for (int n = 0; n < 2; ++n) _Pragma("unroll") for (int k = 0; k < 2; ++k) dst[n][k] = *(const PG8_LAS bf16x8*)(lds + PG8_SB(b, h) + boff + n * 2048 + k * 1024); } while (0)
; #define PG8_WAIT_V(n) asm volatile("s_waitcnt vmcnt(" #n ")" ::: "memory")
; #define PG8_WAIT_L(n) asm volatile("s_waitcnt lgkmcnt(" #n ")" ::: "memory")
; #define PG8_BAR __builtin_amdgcn_s_barrier()
; #define PG8_SCHED __builtin_amdgcn_sched_barrier(0)
; template <class Epi, class Sched, bool ALIGN_EPI = false, bool SP2 = false, bool TA = true>
; __device__ __forceinline__ void gemm_phase(PG8_LAS unsigned char* lds, const Gemm g, const Sched& S, const Epi& E) {
;     ...
;         const char* nA = has_next ? (const char*)g.A + (size_t)nxt.pm * tstep : cA; const char* nB = has_next ? (const char*)g.Bt + (size_t)nxt.pn * tstep : cB;
; #pragma unroll 1
;         for (int t = 0; t < nt; t += 2) {
;             const bool last = (t == nt - 2);
;             const char* a1 = cA + (size_t)(t + 1) * kstep;
;             const char* a2 = last ? nA : cA + (size_t)(t + 2) * kstep; const char* b2 = last ? nB : cB + (size_t)(t + 2) * kstepB;
;             const char* a3 = a2 + kstep; const char* b3 = b2 + kstepB;
;             if (last && has_next) S.a_ready(nxt);
;             if constexpr (SP2) {
;             PG8_LDB(B0, 0, 0); PG8_LDB(B1, 0, 1); PG8_SCHED; PG8_LDA(At, 0, 0); PG8_STAGE(PG8_SA(1, 1), a1 + hstep, voffA);
;             PG8_WAIT_V(8); PG8_WAIT_L(0); PG8_BAR; PG8_MMA(0, 0, At, B0); PG8_MMA(0, 1, At, B1); PG8_BAR; PG8_SCHED;
;             PG8_LDA(At, 0, 1); PG8_STAGE(PG8_SB(0, 0), b2, voffB); PG8_STAGE(PG8_SB(0, 1), b2 + hstep, voffB); PG8_STAGE(PG8_SA(0, 0), a2, voffA);
;             PG8_WAIT_V(8); PG8_WAIT_L(0); PG8_BAR; PG8_MMA(1, 0, At, B0); PG8_MMA(1, 1, At, B1); PG8_BAR; PG8_SCHED;
.LBB0_999:
	s_ashr_i32 s69, s68, 31
	s_lshl_b64 s[70:71], s[68:69], 19
	s_add_u32 s70, s34, s70
	s_addc_u32 s71, s35, s71
	s_and_b64 s[72:73], s[6:7], exec
	s_cselect_b32 s69, s71, s77
	s_cselect_b32 s75, s70, s76
	s_ashr_i32 s61, s60, 31
	s_lshl_b64 s[72:73], s[60:61], 19
	s_add_u32 s72, s33, s72
	s_addc_u32 s73, s93, s73
	s_and_b64 s[98:99], s[6:7], exec
	s_cselect_b32 s61, s73, s79
	s_cselect_b32 s80, s72, s78
	s_waitcnt vmcnt(8)
	s_waitcnt lgkmcnt(0)
	s_barrier
	s_setprio 1
	s_waitcnt lgkmcnt(0)
	v_mfma_f32_16x16x32_bf16 v[124:127], v[128:131], v[180:183], 0
	v_mfma_f32_16x16x32_bf16 v[120:123], v[136:139], v[180:183], 0
	v_mfma_f32_16x16x32_bf16 v[108:111], v[128:131], v[188:191], 0
	v_mfma_f32_16x16x32_bf16 v[104:107], v[136:139], v[188:191], 0
	v_mfma_f32_16x16x32_bf16 v[92:95], v[128:131], v[196:199], 0
	v_mfma_f32_16x16x32_bf16 v[88:91], v[136:139], v[196:199], 0
	v_mfma_f32_16x16x32_bf16 v[76:79], v[128:131], v[204:207], 0
	v_mfma_f32_16x16x32_bf16 v[72:75], v[136:139], v[204:207], 0
	v_mfma_f32_16x16x32_bf16 v[124:127], v[132:135], v[184:187], v[124:127]
	v_mfma_f32_16x16x32_bf16 v[120:123], v[140:143], v[184:187], v[120:123]
	v_mfma_f32_16x16x32_bf16 v[108:111], v[132:135], v[192:195], v[108:111]
	v_mfma_f32_16x16x32_bf16 v[104:107], v[140:143], v[192:195], v[104:107]
	v_mfma_f32_16x16x32_bf16 v[92:95], v[132:135], v[200:203], v[92:95]
	v_mfma_f32_16x16x32_bf16 v[88:91], v[140:143], v[200:203], v[88:91]
	v_mfma_f32_16x16x32_bf16 v[76:79], v[132:135], v[210:213], v[76:79]
	v_mfma_f32_16x16x32_bf16 v[72:75], v[140:143], v[210:213], v[72:75]
	s_setprio 0
	s_setprio 1
	v_mfma_f32_16x16x32_bf16 v[116:119], v[152:155], v[180:183], 0
	v_mfma_f32_16x16x32_bf16 v[112:115], v[172:175], v[180:183], 0
	v_mfma_f32_16x16x32_bf16 v[100:103], v[152:155], v[188:191], 0
	v_mfma_f32_16x16x32_bf16 v[96:99], v[172:175], v[188:191], 0
	v_mfma_f32_16x16x32_bf16 v[84:87], v[152:155], v[196:199], 0
	v_mfma_f32_16x16x32_bf16 v[80:83], v[172:175], v[196:199], 0
	v_mfma_f32_16x16x32_bf16 v[68:71], v[152:155], v[204:207], 0
	v_mfma_f32_16x16x32_bf16 v[64:67], v[172:175], v[204:207], 0
	v_mfma_f32_16x16x32_bf16 v[116:119], v[168:171], v[184:187], v[116:119]
	v_mfma_f32_16x16x32_bf16 v[112:115], v[176:179], v[184:187], v[112:115]
	v_mfma_f32_16x16x32_bf16 v[100:103], v[168:171], v[192:195], v[100:103]
	v_mfma_f32_16x16x32_bf16 v[96:99], v[176:179], v[192:195], v[96:99]
	v_mfma_f32_16x16x32_bf16 v[84:87], v[168:171], v[200:203], v[84:87]
	v_mfma_f32_16x16x32_bf16 v[80:83], v[176:179], v[200:203], v[80:83]
	v_mfma_f32_16x16x32_bf16 v[68:71], v[168:171], v[210:213], v[68:71]
	v_mfma_f32_16x16x32_bf16 v[64:67], v[176:179], v[210:213], v[64:67]
	s_setprio 0
	s_barrier
	v_lshl_add_u64 v[156:157], s[84:85], 0, v[144:145]
	s_add_i32 s84, s42, s94
	s_mov_b32 m0, s84
	ds_read_b128 v[180:183], v165 offset:16384
	ds_read_b128 v[184:187], v165 offset:17408
	ds_read_b128 v[188:191], v165 offset:18432
	ds_read_b128 v[192:195], v165 offset:19456
	ds_read_b128 v[196:199], v165 offset:20480
	ds_read_b128 v[200:203], v165 offset:21504
	ds_read_b128 v[204:207], v165 offset:22528
	ds_read_b128 v[210:213], v165 offset:23552
	global_load_lds_dwordx4 v[156:157], off
	v_lshl_add_u64 v[214:215], v[156:157], 0, s[12:13]
	s_add_i32 m0, s84, 0x2000
	s_add_i32 s84, s43, s94
	global_load_lds_dwordx4 v[214:215], off
	v_lshl_add_u64 v[214:215], v[156:157], 0, s[14:15]
	s_mov_b32 m0, s84
	s_nop 0
	global_load_lds_dwordx4 v[214:215], off
	v_lshl_add_u64 v[214:215], v[156:157], 0, s[16:17]
	s_add_i32 m0, s84, 0x2000
	s_nop 0
	global_load_lds_dwordx4 v[214:215], off
	v_lshl_add_u64 v[214:215], s[82:83], 0, v[144:145]
	s_mov_b32 m0, s95
	v_lshl_add_u64 v[216:217], v[214:215], 0, s[12:13]
	global_load_lds_dwordx4 v[214:215], off
	s_mov_b32 m0, s96
	s_nop 0
	global_load_lds_dwordx4 v[216:217], off
	s_waitcnt vmcnt(8)
	s_waitcnt lgkmcnt(0)
	s_barrier
	s_setprio 1
	s_waitcnt lgkmcnt(0)
	v_mfma_f32_16x16x32_bf16 v[60:63], v[128:131], v[180:183], 0
	v_mfma_f32_16x16x32_bf16 v[56:59], v[136:139], v[180:183], 0
	v_mfma_f32_16x16x32_bf16 v[44:47], v[128:131], v[188:191], 0
	v_mfma_f32_16x16x32_bf16 v[40:43], v[136:139], v[188:191], 0
	v_mfma_f32_16x16x32_bf16 v[28:31], v[128:131], v[196:199], 0
	v_mfma_f32_16x16x32_bf16 v[24:27], v[136:139], v[196:199], 0
	v_mfma_f32_16x16x32_bf16 v[12:15], v[128:131], v[204:207], 0
	v_mfma_f32_16x16x32_bf16 v[8:11], v[136:139], v[204:207], 0
	v_mfma_f32_16x16x32_bf16 v[60:63], v[132:135], v[184:187], v[60:63]
	v_mfma_f32_16x16x32_bf16 v[56:59], v[140:143], v[184:187], v[56:59]
	v_mfma_f32_16x16x32_bf16 v[44:47], v[132:135], v[192:195], v[44:47]
	v_mfma_f32_16x16x32_bf16 v[40:43], v[140:143], v[192:195], v[40:43]
	v_mfma_f32_16x16x32_bf16 v[28:31], v[132:135], v[200:203], v[28:31]
	v_mfma_f32_16x16x32_bf16 v[24:27], v[140:143], v[200:203], v[24:27]
	v_mfma_f32_16x16x32_bf16 v[12:15], v[132:135], v[210:213], v[12:15]
	v_mfma_f32_16x16x32_bf16 v[8:11], v[140:143], v[210:213], v[8:11]
	s_setprio 0
	s_setprio 1
	v_mfma_f32_16x16x32_bf16 v[52:55], v[152:155], v[180:183], 0
	v_mfma_f32_16x16x32_bf16 v[48:51], v[172:175], v[180:183], 0
	v_mfma_f32_16x16x32_bf16 v[36:39], v[152:155], v[188:191], 0
	v_mfma_f32_16x16x32_bf16 v[32:35], v[172:175], v[188:191], 0
	v_mfma_f32_16x16x32_bf16 v[20:23], v[152:155], v[196:199], 0
	v_mfma_f32_16x16x32_bf16 v[16:19], v[172:175], v[196:199], 0
	v_mfma_f32_16x16x32_bf16 v[4:7], v[152:155], v[204:207], 0
	v_mfma_f32_16x16x32_bf16 v[0:3], v[172:175], v[204:207], 0
	v_mfma_f32_16x16x32_bf16 v[52:55], v[168:171], v[184:187], v[52:55]
	v_mfma_f32_16x16x32_bf16 v[48:51], v[176:179], v[184:187], v[48:51]
	v_mfma_f32_16x16x32_bf16 v[36:39], v[168:171], v[192:195], v[36:39]
	v_mfma_f32_16x16x32_bf16 v[32:35], v[176:179], v[192:195], v[32:35]
	v_mfma_f32_16x16x32_bf16 v[20:23], v[168:171], v[200:203], v[20:23]
	v_mfma_f32_16x16x32_bf16 v[16:19], v[176:179], v[200:203], v[16:19]
	v_mfma_f32_16x16x32_bf16 v[4:7], v[168:171], v[210:213], v[4:7]
	v_mfma_f32_16x16x32_bf16 v[0:3], v[176:179], v[210:213], v[0:3]
	s_setprio 0
	s_barrier
; #define PG8_STAGE(bufoff, gbase, voff) do { _Pragma("unroll") for (int _i = 0; _i < 2; ++_i) \
;         __builtin_amdgcn_global_load_lds((const unsigned*)((const char*)(gbase) + (voff)[_i]), (PG8_LAS unsigned*)(lds + (bufoff) + ldsw + _i * 8192), 16, 0, 0); } while (0)
; #define PG8_LDA(dst, b, h) do { _Pragma("unroll") for (int m = 0; m < 4; ++m) _Pragma("unroll") for (int k = 0; k < 2; ++k) dst[m][k] = *(const PG8_LAS bf16x8*)(lds + PG8_SA(b, h) + aoff + m * 2048 + k * 1024); } while (0)
; #define PG8_LDB(dst, b, h) do { _Pragma("unroll") for (int n = 0; n < 2; ++n) _Pragma("unroll") for (int k = 0; k < 2; ++k) dst[n][k] = *(const PG8_LAS bf16x8*)(lds + PG8_SB(b, h) + boff + n * 2048 + k * 1024); } while (0)
; #define PG8_MMA(ai, bj, At, Bt) do { __builtin_amdgcn_s_setprio(1); _Pragma("unroll") for (int m = 0; m < 4; ++m) _Pragma("unroll") for (int n = 0; n < 2; ++n) _Pragma("unroll") for (int k = 0; k < 2; ++k) \
;         acc[ai][bj][m][n] = __builtin_amdgcn_mfma_f32_16x16x32_bf16(Bt[n][k], At[m][k], acc[ai][bj][m][n], 0, 0, 0); __builtin_amdgcn_s_setprio(0); } while (0)
; #define PG8_WAIT_V(n) asm volatile("s_waitcnt vmcnt(" #n ")" ::: "memory")
; #define PG8_WAIT_L(n) asm volatile("s_waitcnt lgkmcnt(" #n ")" ::: "memory")
; #define PG8_BAR __builtin_amdgcn_s_barrier()
; #define PG8_SCHED __builtin_amdgcn_sched_barrier(0)
; template <class Epi, class Sched, bool ALIGN_EPI = false, bool SP2 = false, bool TA = true>
; __device__ __forceinline__ void gemm_phase(PG8_LAS unsigned char* lds, const Gemm g, const Sched& S, const Epi& E) {
;     ...
;             PG8_LDB(B0, 1, 0); PG8_LDB(B1, 1, 1); PG8_SCHED; PG8_LDA(At, 1, 0); PG8_STAGE(PG8_SA(0, 1), a2 + hstep, voffA);
;             PG8_WAIT_V(8); PG8_WAIT_L(0); PG8_BAR; PG8_MMA(0, 0, At, B0); PG8_MMA(0, 1, At, B1); PG8_BAR; PG8_SCHED;
;             PG8_LDA(At, 1, 1); PG8_STAGE(PG8_SB(1, 0), b3, voffB); PG8_STAGE(PG8_SB(1, 1), b3 + hstep, voffB); PG8_STAGE(PG8_SA(1, 0), a3, voffA);
;             PG8_WAIT_V(8); PG8_WAIT_L(0); PG8_BAR; PG8_MMA(1, 0, At, B0); PG8_MMA(1, 1, At, B1); PG8_BAR; PG8_SCHED;
	s_add_i32 s82, 0, 0x18000
	s_add_i32 s83, 0, 0x1c000
	v_add_u32_e32 v140, s82, v159
	v_add_u32_e32 v146, s83, v159
	ds_read_b128 v[128:131], v140
	ds_read_b128 v[132:135], v140 offset:1024
	ds_read_b128 v[136:139], v140 offset:2048
	ds_read_b128 v[140:143], v140 offset:3072
	ds_read_b128 v[152:155], v146
	ds_read_b128 v[168:171], v146 offset:1024
	ds_read_b128 v[172:175], v146 offset:2048
	ds_read_b128 v[176:179], v146 offset:3072
	s_mov_b32 m0, s97
	v_lshl_add_u64 v[216:217], v[214:215], 0, s[14:15]
	ds_read_b128 v[180:183], v165 offset:32768
	ds_read_b128 v[184:187], v165 offset:33792
	ds_read_b128 v[188:191], v165 offset:34816
	ds_read_b128 v[192:195], v165 offset:35840
	ds_read_b128 v[196:199], v165 offset:36864
	ds_read_b128 v[200:203], v165 offset:37888
	ds_read_b128 v[204:207], v165 offset:38912
	ds_read_b128 v[210:213], v165 offset:39936
	global_load_lds_dwordx4 v[216:217], off
	v_lshl_add_u64 v[216:217], v[214:215], 0, s[16:17]
	s_mov_b32 m0, s92
	s_nop 0
	global_load_lds_dwordx4 v[216:217], off
	s_waitcnt vmcnt(8)
	s_waitcnt lgkmcnt(0)
	s_barrier
	s_setprio 1
	s_waitcnt lgkmcnt(0)
	v_mfma_f32_16x16x32_bf16 v[124:127], v[128:131], v[180:183], v[124:127]
	v_mfma_f32_16x16x32_bf16 v[120:123], v[136:139], v[180:183], v[120:123]
	v_mfma_f32_16x16x32_bf16 v[108:111], v[128:131], v[188:191], v[108:111]
	v_mfma_f32_16x16x32_bf16 v[104:107], v[136:139], v[188:191], v[104:107]
	v_mfma_f32_16x16x32_bf16 v[92:95], v[128:131], v[196:199], v[92:95]
	v_mfma_f32_16x16x32_bf16 v[88:91], v[136:139], v[196:199], v[88:91]
	v_mfma_f32_16x16x32_bf16 v[76:79], v[128:131], v[204:207], v[76:79]
	v_mfma_f32_16x16x32_bf16 v[72:75], v[136:139], v[204:207], v[72:75]
	v_mfma_f32_16x16x32_bf16 v[124:127], v[132:135], v[184:187], v[124:127]
	v_mfma_f32_16x16x32_bf16 v[120:123], v[140:143], v[184:187], v[120:123]
	v_mfma_f32_16x16x32_bf16 v[108:111], v[132:135], v[192:195], v[108:111]
	v_mfma_f32_16x16x32_bf16 v[104:107], v[140:143], v[192:195], v[104:107]
	v_mfma_f32_16x16x32_bf16 v[92:95], v[132:135], v[200:203], v[92:95]
	v_mfma_f32_16x16x32_bf16 v[88:91], v[140:143], v[200:203], v[88:91]
	v_mfma_f32_16x16x32_bf16 v[76:79], v[132:135], v[210:213], v[76:79]
	v_mfma_f32_16x16x32_bf16 v[72:75], v[140:143], v[210:213], v[72:75]
	s_setprio 0
	s_setprio 1
	v_mfma_f32_16x16x32_bf16 v[116:119], v[152:155], v[180:183], v[116:119]
	v_mfma_f32_16x16x32_bf16 v[112:115], v[172:175], v[180:183], v[112:115]
	v_mfma_f32_16x16x32_bf16 v[100:103], v[152:155], v[188:191], v[100:103]
	v_mfma_f32_16x16x32_bf16 v[96:99], v[172:175], v[188:191], v[96:99]
	v_mfma_f32_16x16x32_bf16 v[84:87], v[152:155], v[196:199], v[84:87]
	v_mfma_f32_16x16x32_bf16 v[80:83], v[172:175], v[196:199], v[80:83]
	v_mfma_f32_16x16x32_bf16 v[68:71], v[152:155], v[204:207], v[68:71]
	v_mfma_f32_16x16x32_bf16 v[64:67], v[172:175], v[204:207], v[64:67]
	v_mfma_f32_16x16x32_bf16 v[116:119], v[168:171], v[184:187], v[116:119]
	v_mfma_f32_16x16x32_bf16 v[112:115], v[176:179], v[184:187], v[112:115]
	v_mfma_f32_16x16x32_bf16 v[100:103], v[168:171], v[192:195], v[100:103]
	v_mfma_f32_16x16x32_bf16 v[96:99], v[176:179], v[192:195], v[96:99]
	v_mfma_f32_16x16x32_bf16 v[84:87], v[168:171], v[200:203], v[84:87]
	v_mfma_f32_16x16x32_bf16 v[80:83], v[176:179], v[200:203], v[80:83]
	v_mfma_f32_16x16x32_bf16 v[68:71], v[168:171], v[210:213], v[68:71]
	v_mfma_f32_16x16x32_bf16 v[64:67], v[176:179], v[210:213], v[64:67]
	s_setprio 0
	s_barrier
	s_add_i32 s82, s82, s94
	v_lshl_add_u64 v[216:217], v[156:157], 0, s[50:51]
	s_mov_b32 m0, s82
	ds_read_b128 v[180:183], v165 offset:49152
	ds_read_b128 v[184:187], v165 offset:50176
	ds_read_b128 v[188:191], v165 offset:51200
	ds_read_b128 v[192:195], v165 offset:52224
	ds_read_b128 v[196:199], v165 offset:53248
	ds_read_b128 v[200:203], v165 offset:54272
	ds_read_b128 v[204:207], v165 offset:55296
	ds_read_b128 v[210:213], v165 offset:56320
	global_load_lds_dwordx4 v[216:217], off
	v_lshl_add_u64 v[216:217], v[156:157], 0, s[52:53]
	s_add_i32 m0, s82, 0x2000
	s_add_i32 s82, s83, s94
	global_load_lds_dwordx4 v[216:217], off
	v_lshl_add_u64 v[216:217], v[156:157], 0, s[54:55]
	s_mov_b32 m0, s82
	v_lshl_add_u64 v[156:157], v[156:157], 0, s[56:57]
	global_load_lds_dwordx4 v[216:217], off
	s_add_i32 m0, s82, 0x2000
	s_nop 0
	global_load_lds_dwordx4 v[156:157], off
	v_lshl_add_u64 v[156:157], v[214:215], 0, s[50:51]
	s_mov_b32 m0, s18
	s_nop 0
	global_load_lds_dwordx4 v[156:157], off
	v_lshl_add_u64 v[156:157], v[214:215], 0, s[52:53]
	s_mov_b32 m0, s19
	s_nop 0
	global_load_lds_dwordx4 v[156:157], off
	s_waitcnt vmcnt(8)
	s_waitcnt lgkmcnt(0)
	s_barrier
	s_setprio 1
	s_waitcnt lgkmcnt(0)
	v_mfma_f32_16x16x32_bf16 v[60:63], v[128:131], v[180:183], v[60:63]
	v_mfma_f32_16x16x32_bf16 v[56:59], v[136:139], v[180:183], v[56:59]
	v_mfma_f32_16x16x32_bf16 v[44:47], v[128:131], v[188:191], v[44:47]
	v_mfma_f32_16x16x32_bf16 v[40:43], v[136:139], v[188:191], v[40:43]
	v_mfma_f32_16x16x32_bf16 v[28:31], v[128:131], v[196:199], v[28:31]
	v_mfma_f32_16x16x32_bf16 v[24:27], v[136:139], v[196:199], v[24:27]
	v_mfma_f32_16x16x32_bf16 v[12:15], v[128:131], v[204:207], v[12:15]
	v_mfma_f32_16x16x32_bf16 v[8:11], v[136:139], v[204:207], v[8:11]
	v_mfma_f32_16x16x32_bf16 v[60:63], v[132:135], v[184:187], v[60:63]
	v_mfma_f32_16x16x32_bf16 v[56:59], v[140:143], v[184:187], v[56:59]
	v_mfma_f32_16x16x32_bf16 v[44:47], v[132:135], v[192:195], v[44:47]
	v_mfma_f32_16x16x32_bf16 v[40:43], v[140:143], v[192:195], v[40:43]
	v_mfma_f32_16x16x32_bf16 v[28:31], v[132:135], v[200:203], v[28:31]
	v_mfma_f32_16x16x32_bf16 v[24:27], v[140:143], v[200:203], v[24:27]
	v_mfma_f32_16x16x32_bf16 v[12:15], v[132:135], v[210:213], v[12:15]
	v_mfma_f32_16x16x32_bf16 v[8:11], v[140:143], v[210:213], v[8:11]
	s_setprio 0
	s_setprio 1
	v_mfma_f32_16x16x32_bf16 v[52:55], v[152:155], v[180:183], v[52:55]
	v_mfma_f32_16x16x32_bf16 v[48:51], v[172:175], v[180:183], v[48:51]
	v_mfma_f32_16x16x32_bf16 v[36:39], v[152:155], v[188:191], v[36:39]
	v_mfma_f32_16x16x32_bf16 v[32:35], v[172:175], v[188:191], v[32:35]
	v_mfma_f32_16x16x32_bf16 v[20:23], v[152:155], v[196:199], v[20:23]
	v_mfma_f32_16x16x32_bf16 v[16:19], v[172:175], v[196:199], v[16:19]
	v_mfma_f32_16x16x32_bf16 v[4:7], v[152:155], v[204:207], v[4:7]
	v_mfma_f32_16x16x32_bf16 v[0:3], v[172:175], v[204:207], v[0:3]
	v_mfma_f32_16x16x32_bf16 v[52:55], v[168:171], v[184:187], v[52:55]
	v_mfma_f32_16x16x32_bf16 v[48:51], v[176:179], v[184:187], v[48:51]
	v_mfma_f32_16x16x32_bf16 v[36:39], v[168:171], v[192:195], v[36:39]
	v_mfma_f32_16x16x32_bf16 v[32:35], v[176:179], v[192:195], v[32:35]
	v_mfma_f32_16x16x32_bf16 v[20:23], v[168:171], v[200:203], v[20:23]
	v_mfma_f32_16x16x32_bf16 v[16:19], v[176:179], v[200:203], v[16:19]
	v_mfma_f32_16x16x32_bf16 v[4:7], v[168:171], v[210:213], v[4:7]
	v_mfma_f32_16x16x32_bf16 v[0:3], v[176:179], v[210:213], v[0:3]
	s_setprio 0
	s_barrier
	s_add_i32 s81, s81, 2
	s_add_u32 s76, s76, 0x8000
	s_addc_u32 s77, s77, 0
	s_add_u32 s78, s78, 0x8000
	s_addc_u32 s79, s79, 0
	s_cmp_gt_u32 s81, 13

; #define PG8_STAGE(bufoff, gbase, voff) do { _Pragma("unroll") for (int _i = 0; _i < 2; ++_i) \
;         __builtin_amdgcn_global_load_lds((const unsigned*)((const char*)(gbase) + (voff)[_i]), (PG8_LAS unsigned*)(lds + (bufoff) + ldsw + _i * 8192), 16, 0, 0); } while (0)
; #define PG8_LDA(dst, b, h) do { _Pragma("unroll") for (int m = 0; m < 4; ++m) _Pragma("unroll") for (int k = 0; k < 2; ++k) dst[m][k] = *(const PG8_LAS bf16x8*)(lds + PG8_SA(b, h) + aoff + m * 2048 + k * 1024); } while (0)
; #define PG8_LDB(dst, b, h) do { _Pragma("unroll") for (int n = 0; n < 2; ++n) _Pragma("unroll") for (int k = 0; k < 2; ++k) dst[n][k] = *(const PG8_LAS bf16x8*)(lds + PG8_SB(b, h) + boff + n * 2048 + k * 1024); } while (0)
; #define PG8_WAIT_V(n) asm volatile("s_waitcnt vmcnt(" #n ")" ::: "memory")
;     __host__ __device__ bool next(int i, Unit& u) const {
;         const long L = (long)i * G + c; if (L >= nwg) return false;
;         int wgid = (int)L; { const int q = nwg / NXCD, r = nwg % NXCD, xcd = wgid % NXCD, off = wgid / NXCD; wgid = (xcd < r ? xcd * (q + 1) : r * (q + 1) + (xcd - r) * q) + off; }
;         const int nig = WGM * nN, gid = wgid / nig, fm = gid * WGM, gsz = (nM - fm) < WGM ? (nM - fm) : WGM;
;         u.pm = fm + ((wgid % nig) % gsz); u.pn = (wgid % nig) / gsz; return true;
; template <class Epi, class Sched, bool ALIGN_EPI = false, bool SP2 = false, bool TA = true>
; __device__ __forceinline__ void gemm_phase(PG8_LAS unsigned char* lds, const Gemm g, const Sched& S, const Epi& E) {
;     ...
;         const char* nA = has_next ? (const char*)g.A + (size_t)nxt.pm * tstep : cA; const char* nB = has_next ? (const char*)g.Bt + (size_t)nxt.pn * tstep : cB;
; #pragma unroll 1
;         for (int t = 0; t < nt; t += 2) {
;             const bool last = (t == nt - 2);
;             const char* a1 = cA + (size_t)(t + 1) * kstep;
;             const char* a2 = last ? nA : cA + (size_t)(t + 2) * kstep; const char* b2 = last ? nB : cB + (size_t)(t + 2) * kstepB;
;             const char* a3 = a2 + kstep; const char* b3 = b2 + kstepB;
;             if (last && has_next) S.a_ready(nxt);
;             if constexpr (SP2) {
;             PG8_LDB(B0, 0, 0); PG8_LDB(B1, 0, 1); PG8_SCHED; PG8_LDA(At, 0, 0); PG8_STAGE(PG8_SA(1, 1), a1 + hstep, voffA);
;             PG8_WAIT_V(8); PG8_WAIT_L(0); PG8_BAR; PG8_MMA(0, 0, At, B0); PG8_MMA(0, 1, At, B1); PG8_BAR; PG8_SCHED;
.LBB0_1090:
	s_add_u32 s70, s70, 0x44000
	s_addc_u32 s71, s71, 0
	s_add_u32 s72, s72, 0x8000
	s_addc_u32 s73, s73, 0
	s_mov_b32 s78, -2
	ds_read_b128 v[128:131], v189
	ds_read_b128 v[132:135], v189 offset:1024
	ds_read_b128 v[136:139], v189 offset:2048
	s_waitcnt lgkmcnt(0)
	ds_read_b128 v[156:159], v189 offset:3072
	ds_read_b128 v[160:163], v190
	ds_read_b128 v[164:167], v190 offset:1024
	ds_read_b128 v[168:171], v190 offset:2048
	ds_read_b128 v[172:175], v190 offset:3072
	s_add_u32 s79, s70, 0xfffc4000
	s_addc_u32 s80, s71, -1
	s_cmp_eq_u32 s78, 12
	s_cselect_b32 s81, s57, s80
	s_cselect_b32 s80, s69, s79
	s_cselect_b32 s83, s55, s73
	s_cselect_b32 s82, s77, s72
	v_lshl_add_u64 v[218:219], s[70:71], 0, v[140:141]
	s_add_i32 m0, s22, 0xc000
	ds_read_b128 v[176:179], v191
	ds_read_b128 v[180:183], v191 offset:1024
	ds_read_b128 v[184:187], v191 offset:2048
	ds_read_b128 v[196:199], v191 offset:3072
	ds_read_b128 v[200:203], v191 offset:4096
	ds_read_b128 v[204:207], v191 offset:5120
	ds_read_b128 v[210:213], v191 offset:6144
	ds_read_b128 v[214:217], v191 offset:7168
	global_load_lds_dwordx4 v[218:219], off
	v_lshl_add_u64 v[218:219], v[218:219], 0, s[12:13]
	s_add_i32 m0, s22, 0xe000
	s_nop 0
	global_load_lds_dwordx4 v[218:219], off
	s_add_i32 s76, s7, 1
	s_mul_i32 s4, s76, s39
	s_mul_hi_u32 s5, s76, s40
	s_add_i32 s5, s5, s4
	s_mul_i32 s4, s76, s40
	s_add_u32 s58, s4, s20
	s_addc_u32 s59, s5, s41
	v_cmp_gt_i64_e32 vcc, s[58:59], v[154:155]
	v_cmp_lt_i64_e64 s[4:5], s[58:59], v[152:153]
	s_cbranch_vccnz .LBB0_1092
	s_ashr_i32 s54, s58, 31
	s_lshr_b32 s54, s54, 29
	s_add_i32 s54, s58, s54
	s_ashr_i32 s55, s54, 3
	s_and_b32 s54, s54, -8
	s_sub_i32 s54, s58, s54
	s_cmp_lt_i32 s54, 0
	s_cselect_b32 s56, s42, 0xc0
	s_mul_i32 s54, s54, s56
	s_add_i32 s54, s54, s55
	s_mul_hi_i32 s55, s54, 0x2aaaaaab
	s_lshr_b32 s56, s55, 31
	s_ashr_i32 s55, s55, 4
	s_add_i32 s55, s55, s56
	s_lshl_b32 s56, s55, 3
	s_sub_i32 s57, 0x80, s56
	s_min_i32 s57, s57, 8
	s_abs_i32 s58, s57
	v_cvt_f32_u32_e32 v0, s58
	s_sub_i32 s60, 0, s58
	s_mulk_i32 s55, 0x60
	s_sub_i32 s55, s54, s55
	v_rcp_iflag_f32_e32 v0, v0
	s_abs_i32 s54, s55
	s_xor_b32 s59, s55, s57
	s_ashr_i32 s59, s59, 31
	v_mul_f32_e32 v0, 0x4f7ffffe, v0
	v_cvt_u32_f32_e32 v0, v0
	s_nop 0
	v_readfirstlane_b32 s61, v0
	s_mul_i32 s60, s60, s61
	s_mul_hi_u32 s60, s61, s60
	s_add_i32 s61, s61, s60
	s_mul_hi_u32 s60, s54, s61
	s_mul_i32 s61, s60, s58
	s_sub_i32 s54, s54, s61
	s_add_i32 s69, s60, 1
	s_sub_i32 s61, s54, s58
	s_cmp_ge_u32 s54, s58
	s_cselect_b32 s60, s69, s60
	s_cselect_b32 s54, s61, s54
	s_add_i32 s61, s60, 1
	s_cmp_ge_u32 s54, s58
	s_cselect_b32 s54, s61, s60
	s_xor_b32 s54, s54, s59
	s_sub_i32 s54, s54, s59
	s_mul_i32 s57, s54, s57
	s_sub_i32 s55, s55, s57
	s_add_i32 s56, s56, s55
.LBB0_1092:
	s_ashr_i32 s57, s56, 31
	s_lshl_b64 s[58:59], s[56:57], 19
	s_add_u32 s58, s8, s58
	s_addc_u32 s59, s9, s59
	s_and_b64 s[60:61], s[4:5], exec
	s_cselect_b32 s57, s59, s71
	s_cselect_b32 s69, s58, s70
	s_ashr_i32 s55, s54, 31
	s_lshl_b64 s[60:61], s[54:55], 19
	s_add_u32 s60, s18, s60
	s_addc_u32 s61, s19, s61
	s_and_b64 s[98:99], s[4:5], exec
	s_cselect_b32 s55, s61, s73
	s_cselect_b32 s77, s60, s72
	s_waitcnt vmcnt(8)
	s_waitcnt lgkmcnt(0)
	s_barrier
	s_setprio 1
	s_waitcnt lgkmcnt(0)
	v_mfma_f32_16x16x32_bf16 v[124:127], v[128:131], v[176:179], 0
	v_mfma_f32_16x16x32_bf16 v[120:123], v[136:139], v[176:179], 0
	v_mfma_f32_16x16x32_bf16 v[112:115], v[128:131], v[184:187], 0
	v_mfma_f32_16x16x32_bf16 v[104:107], v[136:139], v[184:187], 0
	v_mfma_f32_16x16x32_bf16 v[96:99], v[128:131], v[200:203], 0
	v_mfma_f32_16x16x32_bf16 v[88:91], v[136:139], v[200:203], 0
	v_mfma_f32_16x16x32_bf16 v[80:83], v[128:131], v[210:213], 0
	v_mfma_f32_16x16x32_bf16 v[72:75], v[136:139], v[210:213], 0
	v_mfma_f32_16x16x32_bf16 v[124:127], v[132:135], v[180:183], v[124:127]
	v_mfma_f32_16x16x32_bf16 v[120:123], v[156:159], v[180:183], v[120:123]
	v_mfma_f32_16x16x32_bf16 v[112:115], v[132:135], v[196:199], v[112:115]
	v_mfma_f32_16x16x32_bf16 v[104:107], v[156:159], v[196:199], v[104:107]
	v_mfma_f32_16x16x32_bf16 v[96:99], v[132:135], v[204:207], v[96:99]
	v_mfma_f32_16x16x32_bf16 v[88:91], v[156:159], v[204:207], v[88:91]
	v_mfma_f32_16x16x32_bf16 v[80:83], v[132:135], v[214:217], v[80:83]
	v_mfma_f32_16x16x32_bf16 v[72:75], v[156:159], v[214:217], v[72:75]
	s_setprio 0
	s_setprio 1
	v_mfma_f32_16x16x32_bf16 v[116:119], v[160:163], v[176:179], 0
	v_mfma_f32_16x16x32_bf16 v[108:111], v[168:171], v[176:179], 0
	v_mfma_f32_16x16x32_bf16 v[100:103], v[160:163], v[184:187], 0
	v_mfma_f32_16x16x32_bf16 v[92:95], v[168:171], v[184:187], 0
	v_mfma_f32_16x16x32_bf16 v[84:87], v[160:163], v[200:203], 0
	v_mfma_f32_16x16x32_bf16 v[76:79], v[168:171], v[200:203], 0
	v_mfma_f32_16x16x32_bf16 v[68:71], v[160:163], v[210:213], 0
	v_mfma_f32_16x16x32_bf16 v[64:67], v[168:171], v[210:213], 0
	v_mfma_f32_16x16x32_bf16 v[116:119], v[164:167], v[180:183], v[116:119]
	v_mfma_f32_16x16x32_bf16 v[108:111], v[172:175], v[180:183], v[108:111]
	v_mfma_f32_16x16x32_bf16 v[100:103], v[164:167], v[196:199], v[100:103]
	v_mfma_f32_16x16x32_bf16 v[92:95], v[172:175], v[196:199], v[92:95]
	v_mfma_f32_16x16x32_bf16 v[84:87], v[164:167], v[204:207], v[84:87]
	v_mfma_f32_16x16x32_bf16 v[76:79], v[172:175], v[204:207], v[76:79]
	v_mfma_f32_16x16x32_bf16 v[68:71], v[164:167], v[214:217], v[68:71]
	v_mfma_f32_16x16x32_bf16 v[64:67], v[172:175], v[214:217], v[64:67]
	s_setprio 0
	s_barrier
; #define PG8_STAGE(bufoff, gbase, voff) do { _Pragma("unroll") for (int _i = 0; _i < 2; ++_i) \
;         __builtin_amdgcn_global_load_lds((const unsigned*)((const char*)(gbase) + (voff)[_i]), (PG8_LAS unsigned*)(lds + (bufoff) + ldsw + _i * 8192), 16, 0, 0); } while (0)
; #define PG8_LDA(dst, b, h) do { _Pragma("unroll") for (int m = 0; m < 4; ++m) _Pragma("unroll") for (int k = 0; k < 2; ++k) dst[m][k] = *(const PG8_LAS bf16x8*)(lds + PG8_SA(b, h) + aoff + m * 2048 + k * 1024); } while (0)
; #define PG8_LDB(dst, b, h) do { _Pragma("unroll") for (int n = 0; n < 2; ++n) _Pragma("unroll") for (int k = 0; k < 2; ++k) dst[n][k] = *(const PG8_LAS bf16x8*)(lds + PG8_SB(b, h) + boff + n * 2048 + k * 1024); } while (0)
; #define PG8_MMA(ai, bj, At, Bt) do { __builtin_amdgcn_s_setprio(1); _Pragma("unroll") for (int m = 0; m < 4; ++m) _Pragma("unroll") for (int n = 0; n < 2; ++n) _Pragma("unroll") for (int k = 0; k < 2; ++k) \
;         acc[ai][bj][m][n] = __builtin_amdgcn_mfma_f32_16x16x32_bf16(Bt[n][k], At[m][k], acc[ai][bj][m][n], 0, 0, 0); __builtin_amdgcn_s_setprio(0); } while (0)
; #define PG8_WAIT_V(n) asm volatile("s_waitcnt vmcnt(" #n ")" ::: "memory")
; #define PG8_WAIT_L(n) asm volatile("s_waitcnt lgkmcnt(" #n ")" ::: "memory")
; #define PG8_BAR __builtin_amdgcn_s_barrier()
; #define PG8_SCHED __builtin_amdgcn_sched_barrier(0)
; template <class Epi, class Sched, bool ALIGN_EPI = false, bool SP2 = false, bool TA = true>
; __device__ __forceinline__ void gemm_phase(PG8_LAS unsigned char* lds, const Gemm g, const Sched& S, const Epi& E) {
;     ...
;             PG8_LDA(At, 0, 1); PG8_STAGE(PG8_SB(0, 0), b2, voffB); PG8_STAGE(PG8_SB(0, 1), b2 + hstep, voffB); PG8_STAGE(PG8_SA(0, 0), a2, voffA);
;             PG8_WAIT_V(8); PG8_WAIT_L(0); PG8_BAR; PG8_MMA(1, 0, At, B0); PG8_MMA(1, 1, At, B1); PG8_BAR; PG8_SCHED;
;             PG8_LDB(B0, 1, 0); PG8_LDB(B1, 1, 1); PG8_SCHED; PG8_LDA(At, 1, 0); PG8_STAGE(PG8_SA(0, 1), a2 + hstep, voffA);
	s_add_i32 s79, s43, s21
	v_lshl_add_u64 v[218:219], s[82:83], 0, v[140:141]
	s_mov_b32 m0, s79
	ds_read_b128 v[176:179], v191 offset:16384
	ds_read_b128 v[180:183], v191 offset:17408
	ds_read_b128 v[184:187], v191 offset:18432
	ds_read_b128 v[196:199], v191 offset:19456
	ds_read_b128 v[200:203], v191 offset:20480
	ds_read_b128 v[204:207], v191 offset:21504
	ds_read_b128 v[210:213], v191 offset:22528
	ds_read_b128 v[214:217], v191 offset:23552
	global_load_lds_dwordx4 v[218:219], off
	v_lshl_add_u64 v[220:221], v[218:219], 0, s[12:13]
	s_add_i32 m0, s79, 0x2000
	s_add_i32 s79, s74, s21
	global_load_lds_dwordx4 v[220:221], off
	v_lshl_add_u64 v[220:221], v[218:219], 0, s[14:15]
	s_mov_b32 m0, s79
	s_nop 0
	global_load_lds_dwordx4 v[220:221], off
	v_lshl_add_u64 v[220:221], v[218:219], 0, s[16:17]
	s_add_i32 m0, s79, 0x2000
	s_nop 0
	global_load_lds_dwordx4 v[220:221], off
	v_lshl_add_u64 v[220:221], s[80:81], 0, v[140:141]
	s_mov_b32 m0, s22
	v_lshl_add_u64 v[222:223], v[220:221], 0, s[12:13]
	global_load_lds_dwordx4 v[220:221], off
	s_mov_b32 m0, s23
	s_nop 0
	global_load_lds_dwordx4 v[222:223], off
	s_waitcnt vmcnt(8)
	s_waitcnt lgkmcnt(0)
	s_barrier
	s_setprio 1
	s_waitcnt lgkmcnt(0)
	v_mfma_f32_16x16x32_bf16 v[60:63], v[128:131], v[176:179], 0
	v_mfma_f32_16x16x32_bf16 v[56:59], v[136:139], v[176:179], 0
	v_mfma_f32_16x16x32_bf16 v[48:51], v[128:131], v[184:187], 0
	v_mfma_f32_16x16x32_bf16 v[40:43], v[136:139], v[184:187], 0
	v_mfma_f32_16x16x32_bf16 v[32:35], v[128:131], v[200:203], 0
	v_mfma_f32_16x16x32_bf16 v[24:27], v[136:139], v[200:203], 0
	v_mfma_f32_16x16x32_bf16 v[16:19], v[128:131], v[210:213], 0
	v_mfma_f32_16x16x32_bf16 v[8:11], v[136:139], v[210:213], 0
	v_mfma_f32_16x16x32_bf16 v[60:63], v[132:135], v[180:183], v[60:63]
	v_mfma_f32_16x16x32_bf16 v[56:59], v[156:159], v[180:183], v[56:59]
	v_mfma_f32_16x16x32_bf16 v[48:51], v[132:135], v[196:199], v[48:51]
	v_mfma_f32_16x16x32_bf16 v[40:43], v[156:159], v[196:199], v[40:43]
	v_mfma_f32_16x16x32_bf16 v[32:35], v[132:135], v[204:207], v[32:35]
	v_mfma_f32_16x16x32_bf16 v[24:27], v[156:159], v[204:207], v[24:27]
	v_mfma_f32_16x16x32_bf16 v[16:19], v[132:135], v[214:217], v[16:19]
	v_mfma_f32_16x16x32_bf16 v[8:11], v[156:159], v[214:217], v[8:11]
	s_setprio 0
	s_setprio 1
	v_mfma_f32_16x16x32_bf16 v[52:55], v[160:163], v[176:179], 0
	v_mfma_f32_16x16x32_bf16 v[44:47], v[168:171], v[176:179], 0
	v_mfma_f32_16x16x32_bf16 v[36:39], v[160:163], v[184:187], 0
	v_mfma_f32_16x16x32_bf16 v[28:31], v[168:171], v[184:187], 0
	v_mfma_f32_16x16x32_bf16 v[20:23], v[160:163], v[200:203], 0
	v_mfma_f32_16x16x32_bf16 v[12:15], v[168:171], v[200:203], 0
	v_mfma_f32_16x16x32_bf16 v[4:7], v[160:163], v[210:213], 0
	v_mfma_f32_16x16x32_bf16 v[0:3], v[168:171], v[210:213], 0
	v_mfma_f32_16x16x32_bf16 v[52:55], v[164:167], v[180:183], v[52:55]
	v_mfma_f32_16x16x32_bf16 v[44:47], v[172:175], v[180:183], v[44:47]
	v_mfma_f32_16x16x32_bf16 v[36:39], v[164:167], v[196:199], v[36:39]
	v_mfma_f32_16x16x32_bf16 v[28:31], v[172:175], v[196:199], v[28:31]
	v_mfma_f32_16x16x32_bf16 v[20:23], v[164:167], v[204:207], v[20:23]
	v_mfma_f32_16x16x32_bf16 v[12:15], v[172:175], v[204:207], v[12:15]
	v_mfma_f32_16x16x32_bf16 v[4:7], v[164:167], v[214:217], v[4:7]
	v_mfma_f32_16x16x32_bf16 v[0:3], v[172:175], v[214:217], v[0:3]
	s_setprio 0
	s_barrier
	s_add_i32 s79, 0, 0x18000
	v_add_u32_e32 v142, s79, v147
	s_add_i32 s80, 0, 0x1c000
	ds_read_b128 v[128:131], v142
	ds_read_b128 v[132:135], v142 offset:1024
	ds_read_b128 v[136:139], v142 offset:2048
	ds_read_b128 v[156:159], v142 offset:3072
	v_add_u32_e32 v142, s80, v147
	ds_read_b128 v[160:163], v142
	ds_read_b128 v[164:167], v142 offset:1024
	ds_read_b128 v[168:171], v142 offset:2048
	ds_read_b128 v[172:175], v142 offset:3072
	s_mov_b32 m0, s30
	v_lshl_add_u64 v[222:223], v[220:221], 0, s[14:15]
	ds_read_b128 v[176:179], v191 offset:32768
	ds_read_b128 v[180:183], v191 offset:33792
	ds_read_b128 v[184:187], v191 offset:34816
	ds_read_b128 v[196:199], v191 offset:35840
	ds_read_b128 v[200:203], v191 offset:36864
	ds_read_b128 v[204:207], v191 offset:37888
	ds_read_b128 v[210:213], v191 offset:38912
	ds_read_b128 v[214:217], v191 offset:39936
	global_load_lds_dwordx4 v[222:223], off
	v_lshl_add_u64 v[222:223], v[220:221], 0, s[16:17]
	s_mov_b32 m0, s31
	s_nop 0
	global_load_lds_dwordx4 v[222:223], off
	s_waitcnt vmcnt(8)
	s_waitcnt lgkmcnt(0)
	s_barrier
; #define PG8_STAGE(bufoff, gbase, voff) do { _Pragma("unroll") for (int _i = 0; _i < 2; ++_i) \
;         __builtin_amdgcn_global_load_lds((const unsigned*)((const char*)(gbase) + (voff)[_i]), (PG8_LAS unsigned*)(lds + (bufoff) + ldsw + _i * 8192), 16, 0, 0); } while (0)
; #define PG8_LDA(dst, b, h) do { _Pragma("unroll") for (int m = 0; m < 4; ++m) _Pragma("unroll") for (int k = 0; k < 2; ++k) dst[m][k] = *(const PG8_LAS bf16x8*)(lds + PG8_SA(b, h) + aoff + m * 2048 + k * 1024); } while (0)
; #define PG8_MMA(ai, bj, At, Bt) do { __builtin_amdgcn_s_setprio(1); _Pragma("unroll") for (int m = 0; m < 4; ++m) _Pragma("unroll") for (int n = 0; n < 2; ++n) _Pragma("unroll") for (int k = 0; k < 2; ++k) \
;         acc[ai][bj][m][n] = __builtin_amdgcn_mfma_f32_16x16x32_bf16(Bt[n][k], At[m][k], acc[ai][bj][m][n], 0, 0, 0); __builtin_amdgcn_s_setprio(0); } while (0)
; #define PG8_WAIT_V(n) asm volatile("s_waitcnt vmcnt(" #n ")" ::: "memory")
; #define PG8_WAIT_L(n) asm volatile("s_waitcnt lgkmcnt(" #n ")" ::: "memory")
; #define PG8_BAR __builtin_amdgcn_s_barrier()
; #define PG8_SCHED __builtin_amdgcn_sched_barrier(0)
; template <class Epi, class Sched, bool ALIGN_EPI = false, bool SP2 = false, bool TA = true>
; __device__ __forceinline__ void gemm_phase(PG8_LAS unsigned char* lds, const Gemm g, const Sched& S, const Epi& E) {
;     ...
;             PG8_WAIT_V(8); PG8_WAIT_L(0); PG8_BAR; PG8_MMA(0, 0, At, B0); PG8_MMA(0, 1, At, B1); PG8_BAR; PG8_SCHED;
;             PG8_LDA(At, 1, 1); PG8_STAGE(PG8_SB(1, 0), b3, voffB); PG8_STAGE(PG8_SB(1, 1), b3 + hstep, voffB); PG8_STAGE(PG8_SA(1, 0), a3, voffA);
;             PG8_WAIT_V(8); PG8_WAIT_L(0); PG8_BAR; PG8_MMA(1, 0, At, B0); PG8_MMA(1, 1, At, B1); PG8_BAR; PG8_SCHED;
	s_setprio 1
	s_waitcnt lgkmcnt(0)
	v_mfma_f32_16x16x32_bf16 v[124:127], v[128:131], v[176:179], v[124:127]
	v_mfma_f32_16x16x32_bf16 v[120:123], v[136:139], v[176:179], v[120:123]
	v_mfma_f32_16x16x32_bf16 v[112:115], v[128:131], v[184:187], v[112:115]
	v_mfma_f32_16x16x32_bf16 v[104:107], v[136:139], v[184:187], v[104:107]
	v_mfma_f32_16x16x32_bf16 v[96:99], v[128:131], v[200:203], v[96:99]
	v_mfma_f32_16x16x32_bf16 v[88:91], v[136:139], v[200:203], v[88:91]
	v_mfma_f32_16x16x32_bf16 v[80:83], v[128:131], v[210:213], v[80:83]
	v_mfma_f32_16x16x32_bf16 v[72:75], v[136:139], v[210:213], v[72:75]
	v_mfma_f32_16x16x32_bf16 v[124:127], v[132:135], v[180:183], v[124:127]
	v_mfma_f32_16x16x32_bf16 v[120:123], v[156:159], v[180:183], v[120:123]
	v_mfma_f32_16x16x32_bf16 v[112:115], v[132:135], v[196:199], v[112:115]
	v_mfma_f32_16x16x32_bf16 v[104:107], v[156:159], v[196:199], v[104:107]
	v_mfma_f32_16x16x32_bf16 v[96:99], v[132:135], v[204:207], v[96:99]
	v_mfma_f32_16x16x32_bf16 v[88:91], v[156:159], v[204:207], v[88:91]
	v_mfma_f32_16x16x32_bf16 v[80:83], v[132:135], v[214:217], v[80:83]
	v_mfma_f32_16x16x32_bf16 v[72:75], v[156:159], v[214:217], v[72:75]
	s_setprio 0
	s_setprio 1
	v_mfma_f32_16x16x32_bf16 v[116:119], v[160:163], v[176:179], v[116:119]
	v_mfma_f32_16x16x32_bf16 v[108:111], v[168:171], v[176:179], v[108:111]
	v_mfma_f32_16x16x32_bf16 v[100:103], v[160:163], v[184:187], v[100:103]
	v_mfma_f32_16x16x32_bf16 v[92:95], v[168:171], v[184:187], v[92:95]
	v_mfma_f32_16x16x32_bf16 v[84:87], v[160:163], v[200:203], v[84:87]
	v_mfma_f32_16x16x32_bf16 v[76:79], v[168:171], v[200:203], v[76:79]
	v_mfma_f32_16x16x32_bf16 v[68:71], v[160:163], v[210:213], v[68:71]
	v_mfma_f32_16x16x32_bf16 v[64:67], v[168:171], v[210:213], v[64:67]
	v_mfma_f32_16x16x32_bf16 v[116:119], v[164:167], v[180:183], v[116:119]
	v_mfma_f32_16x16x32_bf16 v[108:111], v[172:175], v[180:183], v[108:111]
	v_mfma_f32_16x16x32_bf16 v[100:103], v[164:167], v[196:199], v[100:103]
	v_mfma_f32_16x16x32_bf16 v[92:95], v[172:175], v[196:199], v[92:95]
	v_mfma_f32_16x16x32_bf16 v[84:87], v[164:167], v[204:207], v[84:87]
	v_mfma_f32_16x16x32_bf16 v[76:79], v[172:175], v[204:207], v[76:79]
	v_mfma_f32_16x16x32_bf16 v[68:71], v[164:167], v[214:217], v[68:71]
	v_mfma_f32_16x16x32_bf16 v[64:67], v[172:175], v[214:217], v[64:67]
	s_setprio 0
	s_barrier
	s_add_i32 s79, s79, s21
	v_lshl_add_u64 v[222:223], v[218:219], 0, s[44:45]
	s_mov_b32 m0, s79
	ds_read_b128 v[176:179], v191 offset:49152
	ds_read_b128 v[180:183], v191 offset:50176
	ds_read_b128 v[184:187], v191 offset:51200
	ds_read_b128 v[196:199], v191 offset:52224
	ds_read_b128 v[200:203], v191 offset:53248
	ds_read_b128 v[204:207], v191 offset:54272
	ds_read_b128 v[210:213], v191 offset:55296
	ds_read_b128 v[214:217], v191 offset:56320
	global_load_lds_dwordx4 v[222:223], off
	v_lshl_add_u64 v[222:223], v[218:219], 0, s[46:47]
	s_add_i32 m0, s79, 0x2000
	s_add_i32 s79, s80, s21
	global_load_lds_dwordx4 v[222:223], off
	v_lshl_add_u64 v[222:223], v[218:219], 0, s[48:49]
	s_mov_b32 m0, s79
	v_lshl_add_u64 v[218:219], v[218:219], 0, s[50:51]
	global_load_lds_dwordx4 v[222:223], off
	s_add_i32 m0, s79, 0x2000
	s_nop 0
	global_load_lds_dwordx4 v[218:219], off
	v_lshl_add_u64 v[218:219], v[220:221], 0, s[44:45]
	s_mov_b32 m0, s33
	s_nop 0
	global_load_lds_dwordx4 v[218:219], off
	v_lshl_add_u64 v[218:219], v[220:221], 0, s[46:47]
	s_mov_b32 m0, s36
	s_nop 0
	global_load_lds_dwordx4 v[218:219], off
	s_waitcnt vmcnt(8)
	s_waitcnt lgkmcnt(0)
	s_barrier
	s_setprio 1
	s_waitcnt lgkmcnt(0)
	v_mfma_f32_16x16x32_bf16 v[60:63], v[128:131], v[176:179], v[60:63]
	v_mfma_f32_16x16x32_bf16 v[56:59], v[136:139], v[176:179], v[56:59]
	v_mfma_f32_16x16x32_bf16 v[48:51], v[128:131], v[184:187], v[48:51]
	v_mfma_f32_16x16x32_bf16 v[40:43], v[136:139], v[184:187], v[40:43]
	v_mfma_f32_16x16x32_bf16 v[32:35], v[128:131], v[200:203], v[32:35]
	v_mfma_f32_16x16x32_bf16 v[24:27], v[136:139], v[200:203], v[24:27]
	v_mfma_f32_16x16x32_bf16 v[16:19], v[128:131], v[210:213], v[16:19]
	v_mfma_f32_16x16x32_bf16 v[8:11], v[136:139], v[210:213], v[8:11]
	v_mfma_f32_16x16x32_bf16 v[60:63], v[132:135], v[180:183], v[60:63]
	v_mfma_f32_16x16x32_bf16 v[56:59], v[156:159], v[180:183], v[56:59]
	v_mfma_f32_16x16x32_bf16 v[48:51], v[132:135], v[196:199], v[48:51]
	v_mfma_f32_16x16x32_bf16 v[40:43], v[156:159], v[196:199], v[40:43]
	v_mfma_f32_16x16x32_bf16 v[32:35], v[132:135], v[204:207], v[32:35]
	v_mfma_f32_16x16x32_bf16 v[24:27], v[156:159], v[204:207], v[24:27]
	v_mfma_f32_16x16x32_bf16 v[16:19], v[132:135], v[214:217], v[16:19]
	v_mfma_f32_16x16x32_bf16 v[8:11], v[156:159], v[214:217], v[8:11]
	s_setprio 0
	s_setprio 1
	v_mfma_f32_16x16x32_bf16 v[52:55], v[160:163], v[176:179], v[52:55]
	v_mfma_f32_16x16x32_bf16 v[44:47], v[168:171], v[176:179], v[44:47]
	v_mfma_f32_16x16x32_bf16 v[36:39], v[160:163], v[184:187], v[36:39]
	v_mfma_f32_16x16x32_bf16 v[28:31], v[168:171], v[184:187], v[28:31]
	v_mfma_f32_16x16x32_bf16 v[20:23], v[160:163], v[200:203], v[20:23]
	v_mfma_f32_16x16x32_bf16 v[12:15], v[168:171], v[200:203], v[12:15]
	v_mfma_f32_16x16x32_bf16 v[4:7], v[160:163], v[210:213], v[4:7]
	v_mfma_f32_16x16x32_bf16 v[0:3], v[168:171], v[210:213], v[0:3]
	v_mfma_f32_16x16x32_bf16 v[52:55], v[164:167], v[180:183], v[52:55]
	v_mfma_f32_16x16x32_bf16 v[44:47], v[172:175], v[180:183], v[44:47]
	v_mfma_f32_16x16x32_bf16 v[36:39], v[164:167], v[196:199], v[36:39]
	v_mfma_f32_16x16x32_bf16 v[28:31], v[172:175], v[196:199], v[28:31]
	v_mfma_f32_16x16x32_bf16 v[20:23], v[164:167], v[204:207], v[20:23]
	v_mfma_f32_16x16x32_bf16 v[12:15], v[172:175], v[204:207], v[12:15]
	v_mfma_f32_16x16x32_bf16 v[4:7], v[164:167], v[214:217], v[4:7]
	v_mfma_f32_16x16x32_bf16 v[0:3], v[172:175], v[214:217], v[0:3]
	s_setprio 0
	s_barrier
	s_add_i32 s78, s78, 2
	s_add_u32 s70, s70, 0x8000
	s_addc_u32 s71, s71, 0
	s_add_u32 s72, s72, 0x8000
	s_addc_u32 s73, s73, 0
	s_cmp_gt_u32 s78, 13

; #define PG8_STAGE(bufoff, gbase, voff) do { _Pragma("unroll") for (int _i = 0; _i < 2; ++_i) \
;         __builtin_amdgcn_global_load_lds((const unsigned*)((const char*)(gbase) + (voff)[_i]), (PG8_LAS unsigned*)(lds + (bufoff) + ldsw + _i * 8192), 16, 0, 0); } while (0)
; #define PG8_LDA(dst, b, h) do { _Pragma("unroll") for (int m = 0; m < 4; ++m) _Pragma("unroll") for (int k = 0; k < 2; ++k) dst[m][k] = *(const PG8_LAS bf16x8*)(lds + PG8_SA(b, h) + aoff + m * 2048 + k * 1024); } while (0)
; #define PG8_LDB(dst, b, h) do { _Pragma("unroll") for (int n = 0; n < 2; ++n) _Pragma("unroll") for (int k = 0; k < 2; ++k) dst[n][k] = *(const PG8_LAS bf16x8*)(lds + PG8_SB(b, h) + boff + n * 2048 + k * 1024); } while (0)
; #define PG8_SCHED __builtin_amdgcn_sched_barrier(0)
;   __device__ __forceinline__ bool next(int i,AttnUnit&u)const{ if(i>=8)return false; const int s=vcu&7,k=i&3; { const int p_=vcu>>3; u.bh=(p_>>3)*16+(p_&7)*2+(i>>2); } u.qb=(k==0)?s:(k==1)?15-s:(k==2)?16+s:31-s; return true; }
;     __host__ __device__ bool next(int i, Unit& u) const {
;         const long L = (long)i * G + c; if (L >= nwg) return false;
;         int wgid = (int)L; { const int q = nwg / NXCD, r = nwg % NXCD, xcd = wgid % NXCD, off = wgid / NXCD; wgid = (xcd < r ? xcd * (q + 1) : r * (q + 1) + (xcd - r) * q) + off; }
;         const int nig = WGM * nN, gid = wgid / nig, fm = gid * WGM, gsz = (nM - fm) < WGM ? (nM - fm) : WGM;
;         u.pm = fm + ((wgid % nig) % gsz); u.pn = (wgid % nig) / gsz; return true;
; template <class Epi, class Sched, bool ALIGN_EPI = false, bool SP2 = false, bool TA = true>
; __device__ __forceinline__ void gemm_phase(PG8_LAS unsigned char* lds, const Gemm g, const Sched& S, const Epi& E) {
;     ...
;             const char* a1 = cA + (size_t)(t + 1) * kstep;
;             const char* a2 = last ? nA : cA + (size_t)(t + 2) * kstep; const char* b2 = last ? nB : cB + (size_t)(t + 2) * kstepB;
;             const char* a3 = a2 + kstep; const char* b3 = b2 + kstepB;
;             if (last && has_next) S.a_ready(nxt);
;             if constexpr (SP2) {
;             PG8_LDB(B0, 0, 0); PG8_LDB(B1, 0, 1); PG8_SCHED; PG8_LDA(At, 0, 0); PG8_STAGE(PG8_SA(1, 1), a1 + hstep, voffA);
.LBB0_1529:
	s_add_u32 s56, s56, 0x44000
	s_addc_u32 s57, s57, 0
	s_add_u32 s58, s58, 0x8000
	s_addc_u32 s59, s59, 0
	s_mov_b32 s61, -2
	s_waitcnt lgkmcnt(0)
	ds_read_b128 v[128:131], v149
	ds_read_b128 v[142:145], v149 offset:1024
	ds_read_b128 v[154:157], v149 offset:2048
	ds_read_b128 v[158:161], v149 offset:3072
	ds_read_b128 v[162:165], v150
	ds_read_b128 v[166:169], v150 offset:1024
	ds_read_b128 v[170:173], v150 offset:2048
	ds_read_b128 v[174:177], v150 offset:3072
	s_add_u32 s62, s56, 0xfffc4000
	s_addc_u32 s63, s57, -1
	s_cmp_eq_u32 s61, 12
	s_cselect_b32 s63, s49, s63
	s_cselect_b32 s62, s55, s62
	s_cselect_b32 s65, s47, s59
	s_cselect_b32 s64, s60, s58
	v_lshl_add_u64 v[132:133], s[56:57], 0, v[134:135]
	s_add_i32 m0, s22, 0xc000
	ds_read_b128 v[178:181], v151
	ds_read_b128 v[182:185], v151 offset:1024
	ds_read_b128 v[186:189], v151 offset:2048
	ds_read_b128 v[190:193], v151 offset:3072
	ds_read_b128 v[194:197], v151 offset:4096
	ds_read_b128 v[198:201], v151 offset:5120
	ds_read_b128 v[202:205], v151 offset:6144
	ds_read_b128 v[210:213], v151 offset:7168
	global_load_lds_dwordx4 v[132:133], off
	v_lshl_add_u64 v[132:133], v[132:133], 0, s[6:7]
	s_add_i32 m0, s22, 0xe000
	s_nop 0
	global_load_lds_dwordx4 v[132:133], off
	s_add_i32 s78, s78, 1
	s_mul_i32 s4, s78, s71
	s_mul_hi_u32 s5, s78, s72
	s_add_i32 s5, s5, s4
	s_mul_i32 s4, s78, s72
	s_add_u32 s50, s4, s20
	s_addc_u32 s51, s5, s73
	v_cmp_gt_i64_e32 vcc, s[50:51], v[140:141]
	v_cmp_lt_i64_e64 s[4:5], s[50:51], v[138:139]
	s_cbranch_vccnz .LBB0_1535
	s_ashr_i32 s46, s50, 31
	s_lshr_b32 s46, s46, 29
	s_add_i32 s48, s50, s46
	s_and_b32 s46, s48, -8
	s_sub_i32 s49, s50, s46
	s_cmp_gt_i32 s49, -1
	s_mov_b64 s[46:47], -1
	s_cbranch_scc0 .LBB0_1532
	s_lshl_b32 s50, s49, 6
	s_mov_b64 s[46:47], 0

; #define PG8_STAGE(bufoff, gbase, voff) do { _Pragma("unroll") for (int _i = 0; _i < 2; ++_i) \
;         __builtin_amdgcn_global_load_lds((const unsigned*)((const char*)(gbase) + (voff)[_i]), (PG8_LAS unsigned*)(lds + (bufoff) + ldsw + _i * 8192), 16, 0, 0); } while (0)
; #define PG8_LDA(dst, b, h) do { _Pragma("unroll") for (int m = 0; m < 4; ++m) _Pragma("unroll") for (int k = 0; k < 2; ++k) dst[m][k] = *(const PG8_LAS bf16x8*)(lds + PG8_SA(b, h) + aoff + m * 2048 + k * 1024); } while (0)
; #define PG8_LDB(dst, b, h) do { _Pragma("unroll") for (int n = 0; n < 2; ++n) _Pragma("unroll") for (int k = 0; k < 2; ++k) dst[n][k] = *(const PG8_LAS bf16x8*)(lds + PG8_SB(b, h) + boff + n * 2048 + k * 1024); } while (0)
; #define PG8_WAIT_V(n) asm volatile("s_waitcnt vmcnt(" #n ")" ::: "memory")
; #define PG8_WAIT_L(n) asm volatile("s_waitcnt lgkmcnt(" #n ")" ::: "memory")
; #define PG8_BAR __builtin_amdgcn_s_barrier()
; #define PG8_SCHED __builtin_amdgcn_sched_barrier(0)
; template <class Epi, class Sched, bool ALIGN_EPI = false, bool SP2 = false, bool TA = true>
; __device__ __forceinline__ void gemm_phase(PG8_LAS unsigned char* lds, const Gemm g, const Sched& S, const Epi& E) {
;     ...
;         const char* nA = has_next ? (const char*)g.A + (size_t)nxt.pm * tstep : cA; const char* nB = has_next ? (const char*)g.Bt + (size_t)nxt.pn * tstep : cB;
; #pragma unroll 1
;         for (int t = 0; t < nt; t += 2) {
;             const bool last = (t == nt - 2);
;             const char* a1 = cA + (size_t)(t + 1) * kstep;
;             const char* a2 = last ? nA : cA + (size_t)(t + 2) * kstep; const char* b2 = last ? nB : cB + (size_t)(t + 2) * kstepB;
;             const char* a3 = a2 + kstep; const char* b3 = b2 + kstepB;
;             if (last && has_next) S.a_ready(nxt);
;             if constexpr (SP2) {
;             PG8_LDB(B0, 0, 0); PG8_LDB(B1, 0, 1); PG8_SCHED; PG8_LDA(At, 0, 0); PG8_STAGE(PG8_SA(1, 1), a1 + hstep, voffA);
;             PG8_WAIT_V(8); PG8_WAIT_L(0); PG8_BAR; PG8_MMA(0, 0, At, B0); PG8_MMA(0, 1, At, B1); PG8_BAR; PG8_SCHED;
;             PG8_LDA(At, 0, 1); PG8_STAGE(PG8_SB(0, 0), b2, voffB); PG8_STAGE(PG8_SB(0, 1), b2 + hstep, voffB); PG8_STAGE(PG8_SA(0, 0), a2, voffA);
;             PG8_WAIT_V(8); PG8_WAIT_L(0); PG8_BAR; PG8_MMA(1, 0, At, B0); PG8_MMA(1, 1, At, B1); PG8_BAR; PG8_SCHED;
.LBB0_1535:
	s_ashr_i32 s49, s48, 31
	s_lshl_b64 s[50:51], s[48:49], 19
	s_add_u32 s50, s34, s50
	s_addc_u32 s51, s35, s51
	s_and_b64 s[52:53], s[4:5], exec
	s_cselect_b32 s49, s51, s57
	s_cselect_b32 s55, s50, s56
	s_ashr_i32 s47, s46, 31
	s_lshl_b64 s[52:53], s[46:47], 19
	s_add_u32 s52, s18, s52
	s_addc_u32 s53, s19, s53
	s_and_b64 s[98:99], s[4:5], exec
	s_cselect_b32 s47, s53, s59
	s_cselect_b32 s60, s52, s58
	s_waitcnt vmcnt(8)
	s_waitcnt lgkmcnt(0)
	s_barrier
	s_setprio 1
	s_waitcnt lgkmcnt(0)
	v_mfma_f32_16x16x32_bf16 v[124:127], v[128:131], v[178:181], 0
	v_mfma_f32_16x16x32_bf16 v[120:123], v[154:157], v[178:181], 0
	v_mfma_f32_16x16x32_bf16 v[108:111], v[128:131], v[186:189], 0
	v_mfma_f32_16x16x32_bf16 v[104:107], v[154:157], v[186:189], 0
	v_mfma_f32_16x16x32_bf16 v[92:95], v[128:131], v[194:197], 0
	v_mfma_f32_16x16x32_bf16 v[88:91], v[154:157], v[194:197], 0
	v_mfma_f32_16x16x32_bf16 v[76:79], v[128:131], v[202:205], 0
	v_mfma_f32_16x16x32_bf16 v[72:75], v[154:157], v[202:205], 0
	v_mfma_f32_16x16x32_bf16 v[124:127], v[142:145], v[182:185], v[124:127]
	v_mfma_f32_16x16x32_bf16 v[120:123], v[158:161], v[182:185], v[120:123]
	v_mfma_f32_16x16x32_bf16 v[108:111], v[142:145], v[190:193], v[108:111]
	v_mfma_f32_16x16x32_bf16 v[104:107], v[158:161], v[190:193], v[104:107]
	v_mfma_f32_16x16x32_bf16 v[92:95], v[142:145], v[198:201], v[92:95]
	v_mfma_f32_16x16x32_bf16 v[88:91], v[158:161], v[198:201], v[88:91]
	v_mfma_f32_16x16x32_bf16 v[76:79], v[142:145], v[210:213], v[76:79]
	v_mfma_f32_16x16x32_bf16 v[72:75], v[158:161], v[210:213], v[72:75]
	s_setprio 0
	s_setprio 1
	v_mfma_f32_16x16x32_bf16 v[116:119], v[162:165], v[178:181], 0
	v_mfma_f32_16x16x32_bf16 v[112:115], v[170:173], v[178:181], 0
	v_mfma_f32_16x16x32_bf16 v[100:103], v[162:165], v[186:189], 0
	v_mfma_f32_16x16x32_bf16 v[96:99], v[170:173], v[186:189], 0
	v_mfma_f32_16x16x32_bf16 v[84:87], v[162:165], v[194:197], 0
	v_mfma_f32_16x16x32_bf16 v[80:83], v[170:173], v[194:197], 0
	v_mfma_f32_16x16x32_bf16 v[68:71], v[162:165], v[202:205], 0
	v_mfma_f32_16x16x32_bf16 v[64:67], v[170:173], v[202:205], 0
	v_mfma_f32_16x16x32_bf16 v[116:119], v[166:169], v[182:185], v[116:119]
	v_mfma_f32_16x16x32_bf16 v[112:115], v[174:177], v[182:185], v[112:115]
	v_mfma_f32_16x16x32_bf16 v[100:103], v[166:169], v[190:193], v[100:103]
	v_mfma_f32_16x16x32_bf16 v[96:99], v[174:177], v[190:193], v[96:99]
	v_mfma_f32_16x16x32_bf16 v[84:87], v[166:169], v[198:201], v[84:87]
	v_mfma_f32_16x16x32_bf16 v[80:83], v[174:177], v[198:201], v[80:83]
	v_mfma_f32_16x16x32_bf16 v[68:71], v[166:169], v[210:213], v[68:71]
	v_mfma_f32_16x16x32_bf16 v[64:67], v[174:177], v[210:213], v[64:67]
	s_setprio 0
	s_barrier
	v_lshl_add_u64 v[132:133], s[64:65], 0, v[134:135]
	s_add_i32 s64, s76, s21
	s_mov_b32 m0, s64
	ds_read_b128 v[178:181], v151 offset:16384
	ds_read_b128 v[182:185], v151 offset:17408
	ds_read_b128 v[186:189], v151 offset:18432
	ds_read_b128 v[190:193], v151 offset:19456
	ds_read_b128 v[194:197], v151 offset:20480
	ds_read_b128 v[198:201], v151 offset:21504
	ds_read_b128 v[202:205], v151 offset:22528
	ds_read_b128 v[210:213], v151 offset:23552
	global_load_lds_dwordx4 v[132:133], off
	v_lshl_add_u64 v[206:207], v[132:133], 0, s[6:7]
	s_add_i32 m0, s64, 0x2000
	s_add_i32 s64, s77, s21
	global_load_lds_dwordx4 v[206:207], off
	v_lshl_add_u64 v[206:207], v[132:133], 0, s[12:13]
	s_mov_b32 m0, s64
	s_nop 0
	global_load_lds_dwordx4 v[206:207], off
	v_lshl_add_u64 v[206:207], v[132:133], 0, s[14:15]
	s_add_i32 m0, s64, 0x2000
	s_nop 0
	global_load_lds_dwordx4 v[206:207], off
	v_lshl_add_u64 v[206:207], s[62:63], 0, v[134:135]
	s_mov_b32 m0, s22
	v_lshl_add_u64 v[214:215], v[206:207], 0, s[6:7]
	global_load_lds_dwordx4 v[206:207], off
	s_mov_b32 m0, s23
	s_nop 0
	global_load_lds_dwordx4 v[214:215], off
	s_waitcnt vmcnt(8)
	s_waitcnt lgkmcnt(0)
	s_barrier
	s_setprio 1
	s_waitcnt lgkmcnt(0)
	v_mfma_f32_16x16x32_bf16 v[60:63], v[128:131], v[178:181], 0
	v_mfma_f32_16x16x32_bf16 v[56:59], v[154:157], v[178:181], 0
	v_mfma_f32_16x16x32_bf16 v[44:47], v[128:131], v[186:189], 0
	v_mfma_f32_16x16x32_bf16 v[40:43], v[154:157], v[186:189], 0
	v_mfma_f32_16x16x32_bf16 v[28:31], v[128:131], v[194:197], 0
	v_mfma_f32_16x16x32_bf16 v[24:27], v[154:157], v[194:197], 0
	v_mfma_f32_16x16x32_bf16 v[12:15], v[128:131], v[202:205], 0
	v_mfma_f32_16x16x32_bf16 v[8:11], v[154:157], v[202:205], 0
	v_mfma_f32_16x16x32_bf16 v[60:63], v[142:145], v[182:185], v[60:63]
	v_mfma_f32_16x16x32_bf16 v[56:59], v[158:161], v[182:185], v[56:59]
	v_mfma_f32_16x16x32_bf16 v[44:47], v[142:145], v[190:193], v[44:47]
	v_mfma_f32_16x16x32_bf16 v[40:43], v[158:161], v[190:193], v[40:43]
	v_mfma_f32_16x16x32_bf16 v[28:31], v[142:145], v[198:201], v[28:31]
	v_mfma_f32_16x16x32_bf16 v[24:27], v[158:161], v[198:201], v[24:27]
	v_mfma_f32_16x16x32_bf16 v[12:15], v[142:145], v[210:213], v[12:15]
	v_mfma_f32_16x16x32_bf16 v[8:11], v[158:161], v[210:213], v[8:11]
	s_setprio 0
	s_setprio 1
	v_mfma_f32_16x16x32_bf16 v[52:55], v[162:165], v[178:181], 0
	v_mfma_f32_16x16x32_bf16 v[48:51], v[170:173], v[178:181], 0
	v_mfma_f32_16x16x32_bf16 v[36:39], v[162:165], v[186:189], 0
	v_mfma_f32_16x16x32_bf16 v[32:35], v[170:173], v[186:189], 0
	v_mfma_f32_16x16x32_bf16 v[20:23], v[162:165], v[194:197], 0
	v_mfma_f32_16x16x32_bf16 v[16:19], v[170:173], v[194:197], 0
	v_mfma_f32_16x16x32_bf16 v[4:7], v[162:165], v[202:205], 0
	v_mfma_f32_16x16x32_bf16 v[0:3], v[170:173], v[202:205], 0
	v_mfma_f32_16x16x32_bf16 v[52:55], v[166:169], v[182:185], v[52:55]
	v_mfma_f32_16x16x32_bf16 v[48:51], v[174:177], v[182:185], v[48:51]
	v_mfma_f32_16x16x32_bf16 v[36:39], v[166:169], v[190:193], v[36:39]
	v_mfma_f32_16x16x32_bf16 v[32:35], v[174:177], v[190:193], v[32:35]
	v_mfma_f32_16x16x32_bf16 v[20:23], v[166:169], v[198:201], v[20:23]
	v_mfma_f32_16x16x32_bf16 v[16:19], v[174:177], v[198:201], v[16:19]
	v_mfma_f32_16x16x32_bf16 v[4:7], v[166:169], v[210:213], v[4:7]
	v_mfma_f32_16x16x32_bf16 v[0:3], v[174:177], v[210:213], v[0:3]
	s_setprio 0
	s_barrier
; #define PG8_STAGE(bufoff, gbase, voff) do { _Pragma("unroll") for (int _i = 0; _i < 2; ++_i) \
;         __builtin_amdgcn_global_load_lds((const unsigned*)((const char*)(gbase) + (voff)[_i]), (PG8_LAS unsigned*)(lds + (bufoff) + ldsw + _i * 8192), 16, 0, 0); } while (0)
; #define PG8_LDA(dst, b, h) do { _Pragma("unroll") for (int m = 0; m < 4; ++m) _Pragma("unroll") for (int k = 0; k < 2; ++k) dst[m][k] = *(const PG8_LAS bf16x8*)(lds + PG8_SA(b, h) + aoff + m * 2048 + k * 1024); } while (0)
; #define PG8_LDB(dst, b, h) do { _Pragma("unroll") for (int n = 0; n < 2; ++n) _Pragma("unroll") for (int k = 0; k < 2; ++k) dst[n][k] = *(const PG8_LAS bf16x8*)(lds + PG8_SB(b, h) + boff + n * 2048 + k * 1024); } while (0)
; #define PG8_MMA(ai, bj, At, Bt) do { __builtin_amdgcn_s_setprio(1); _Pragma("unroll") for (int m = 0; m < 4; ++m) _Pragma("unroll") for (int n = 0; n < 2; ++n) _Pragma("unroll") for (int k = 0; k < 2; ++k) \
;         acc[ai][bj][m][n] = __builtin_amdgcn_mfma_f32_16x16x32_bf16(Bt[n][k], At[m][k], acc[ai][bj][m][n], 0, 0, 0); __builtin_amdgcn_s_setprio(0); } while (0)
; #define PG8_WAIT_V(n) asm volatile("s_waitcnt vmcnt(" #n ")" ::: "memory")
; #define PG8_WAIT_L(n) asm volatile("s_waitcnt lgkmcnt(" #n ")" ::: "memory")
; #define PG8_BAR __builtin_amdgcn_s_barrier()
; #define PG8_SCHED __builtin_amdgcn_sched_barrier(0)
; template <class Epi, class Sched, bool ALIGN_EPI = false, bool SP2 = false, bool TA = true>
; __device__ __forceinline__ void gemm_phase(PG8_LAS unsigned char* lds, const Gemm g, const Sched& S, const Epi& E) {
;     ...
;             PG8_LDB(B0, 1, 0); PG8_LDB(B1, 1, 1); PG8_SCHED; PG8_LDA(At, 1, 0); PG8_STAGE(PG8_SA(0, 1), a2 + hstep, voffA);
;             PG8_WAIT_V(8); PG8_WAIT_L(0); PG8_BAR; PG8_MMA(0, 0, At, B0); PG8_MMA(0, 1, At, B1); PG8_BAR; PG8_SCHED;
;             PG8_LDA(At, 1, 1); PG8_STAGE(PG8_SB(1, 0), b3, voffB); PG8_STAGE(PG8_SB(1, 1), b3 + hstep, voffB); PG8_STAGE(PG8_SA(1, 0), a3, voffA);
;             PG8_WAIT_V(8); PG8_WAIT_L(0); PG8_BAR; PG8_MMA(1, 0, At, B0); PG8_MMA(1, 1, At, B1); PG8_BAR; PG8_SCHED;
	s_add_i32 s62, 0, 0x18000
	v_add_u32_e32 v136, s62, v148
	s_add_i32 s63, 0, 0x1c000
	ds_read_b128 v[128:131], v136
	ds_read_b128 v[142:145], v136 offset:1024
	ds_read_b128 v[154:157], v136 offset:2048
	ds_read_b128 v[158:161], v136 offset:3072
	v_add_u32_e32 v136, s63, v148
	ds_read_b128 v[162:165], v136
	ds_read_b128 v[166:169], v136 offset:1024
	ds_read_b128 v[170:173], v136 offset:2048
	ds_read_b128 v[174:177], v136 offset:3072
	s_mov_b32 m0, s30
	v_lshl_add_u64 v[214:215], v[206:207], 0, s[12:13]
	ds_read_b128 v[178:181], v151 offset:32768
	ds_read_b128 v[182:185], v151 offset:33792
	ds_read_b128 v[186:189], v151 offset:34816
	ds_read_b128 v[190:193], v151 offset:35840
	ds_read_b128 v[194:197], v151 offset:36864
	ds_read_b128 v[198:201], v151 offset:37888
	ds_read_b128 v[202:205], v151 offset:38912
	ds_read_b128 v[210:213], v151 offset:39936
	global_load_lds_dwordx4 v[214:215], off
	v_lshl_add_u64 v[214:215], v[206:207], 0, s[14:15]
	s_mov_b32 m0, s31
	s_nop 0
	global_load_lds_dwordx4 v[214:215], off
	s_waitcnt vmcnt(8)
	s_waitcnt lgkmcnt(0)
	s_barrier
	s_setprio 1
	s_waitcnt lgkmcnt(0)
	v_mfma_f32_16x16x32_bf16 v[124:127], v[128:131], v[178:181], v[124:127]
	v_mfma_f32_16x16x32_bf16 v[120:123], v[154:157], v[178:181], v[120:123]
	v_mfma_f32_16x16x32_bf16 v[108:111], v[128:131], v[186:189], v[108:111]
	v_mfma_f32_16x16x32_bf16 v[104:107], v[154:157], v[186:189], v[104:107]
	v_mfma_f32_16x16x32_bf16 v[92:95], v[128:131], v[194:197], v[92:95]
	v_mfma_f32_16x16x32_bf16 v[88:91], v[154:157], v[194:197], v[88:91]
	v_mfma_f32_16x16x32_bf16 v[76:79], v[128:131], v[202:205], v[76:79]
	v_mfma_f32_16x16x32_bf16 v[72:75], v[154:157], v[202:205], v[72:75]
	v_mfma_f32_16x16x32_bf16 v[124:127], v[142:145], v[182:185], v[124:127]
	v_mfma_f32_16x16x32_bf16 v[120:123], v[158:161], v[182:185], v[120:123]
	v_mfma_f32_16x16x32_bf16 v[108:111], v[142:145], v[190:193], v[108:111]
	v_mfma_f32_16x16x32_bf16 v[104:107], v[158:161], v[190:193], v[104:107]
	v_mfma_f32_16x16x32_bf16 v[92:95], v[142:145], v[198:201], v[92:95]
	v_mfma_f32_16x16x32_bf16 v[88:91], v[158:161], v[198:201], v[88:91]
	v_mfma_f32_16x16x32_bf16 v[76:79], v[142:145], v[210:213], v[76:79]
	v_mfma_f32_16x16x32_bf16 v[72:75], v[158:161], v[210:213], v[72:75]
	s_setprio 0
	s_setprio 1
	v_mfma_f32_16x16x32_bf16 v[116:119], v[162:165], v[178:181], v[116:119]
	v_mfma_f32_16x16x32_bf16 v[112:115], v[170:173], v[178:181], v[112:115]
	v_mfma_f32_16x16x32_bf16 v[100:103], v[162:165], v[186:189], v[100:103]
	v_mfma_f32_16x16x32_bf16 v[96:99], v[170:173], v[186:189], v[96:99]
	v_mfma_f32_16x16x32_bf16 v[84:87], v[162:165], v[194:197], v[84:87]
	v_mfma_f32_16x16x32_bf16 v[80:83], v[170:173], v[194:197], v[80:83]
	v_mfma_f32_16x16x32_bf16 v[68:71], v[162:165], v[202:205], v[68:71]
	v_mfma_f32_16x16x32_bf16 v[64:67], v[170:173], v[202:205], v[64:67]
	v_mfma_f32_16x16x32_bf16 v[116:119], v[166:169], v[182:185], v[116:119]
	v_mfma_f32_16x16x32_bf16 v[112:115], v[174:177], v[182:185], v[112:115]
	v_mfma_f32_16x16x32_bf16 v[100:103], v[166:169], v[190:193], v[100:103]
	v_mfma_f32_16x16x32_bf16 v[96:99], v[174:177], v[190:193], v[96:99]
	v_mfma_f32_16x16x32_bf16 v[84:87], v[166:169], v[198:201], v[84:87]
	v_mfma_f32_16x16x32_bf16 v[80:83], v[174:177], v[198:201], v[80:83]
	v_mfma_f32_16x16x32_bf16 v[68:71], v[166:169], v[210:213], v[68:71]
	v_mfma_f32_16x16x32_bf16 v[64:67], v[174:177], v[210:213], v[64:67]
	s_setprio 0
	s_barrier
	s_add_i32 s62, s62, s21
	v_lshl_add_u64 v[214:215], v[132:133], 0, s[36:37]
	s_mov_b32 m0, s62
	ds_read_b128 v[178:181], v151 offset:49152
	ds_read_b128 v[182:185], v151 offset:50176
	ds_read_b128 v[186:189], v151 offset:51200
	ds_read_b128 v[190:193], v151 offset:52224
	ds_read_b128 v[194:197], v151 offset:53248
	ds_read_b128 v[198:201], v151 offset:54272
	ds_read_b128 v[202:205], v151 offset:55296
	ds_read_b128 v[210:213], v151 offset:56320
	global_load_lds_dwordx4 v[214:215], off
	v_lshl_add_u64 v[214:215], v[132:133], 0, s[38:39]
	s_add_i32 m0, s62, 0x2000
	s_add_i32 s62, s63, s21
	global_load_lds_dwordx4 v[214:215], off
	v_lshl_add_u64 v[214:215], v[132:133], 0, s[40:41]
	s_mov_b32 m0, s62
	v_lshl_add_u64 v[132:133], v[132:133], 0, s[42:43]
	global_load_lds_dwordx4 v[214:215], off
	s_add_i32 m0, s62, 0x2000
	s_nop 0
	global_load_lds_dwordx4 v[132:133], off
	v_lshl_add_u64 v[132:133], v[206:207], 0, s[36:37]
	s_mov_b32 m0, s33
	s_nop 0
	global_load_lds_dwordx4 v[132:133], off
	v_lshl_add_u64 v[132:133], v[206:207], 0, s[38:39]
	s_mov_b32 m0, s66
	s_nop 0
	global_load_lds_dwordx4 v[132:133], off
	s_waitcnt vmcnt(8)
	s_waitcnt lgkmcnt(0)
	s_barrier
	s_setprio 1
	s_waitcnt lgkmcnt(0)
	v_mfma_f32_16x16x32_bf16 v[60:63], v[128:131], v[178:181], v[60:63]
	v_mfma_f32_16x16x32_bf16 v[56:59], v[154:157], v[178:181], v[56:59]
	v_mfma_f32_16x16x32_bf16 v[44:47], v[128:131], v[186:189], v[44:47]
	v_mfma_f32_16x16x32_bf16 v[40:43], v[154:157], v[186:189], v[40:43]
	v_mfma_f32_16x16x32_bf16 v[28:31], v[128:131], v[194:197], v[28:31]
	v_mfma_f32_16x16x32_bf16 v[24:27], v[154:157], v[194:197], v[24:27]
	v_mfma_f32_16x16x32_bf16 v[12:15], v[128:131], v[202:205], v[12:15]
	v_mfma_f32_16x16x32_bf16 v[8:11], v[154:157], v[202:205], v[8:11]
	v_mfma_f32_16x16x32_bf16 v[60:63], v[142:145], v[182:185], v[60:63]
	v_mfma_f32_16x16x32_bf16 v[56:59], v[158:161], v[182:185], v[56:59]
	v_mfma_f32_16x16x32_bf16 v[44:47], v[142:145], v[190:193], v[44:47]
	v_mfma_f32_16x16x32_bf16 v[40:43], v[158:161], v[190:193], v[40:43]
	v_mfma_f32_16x16x32_bf16 v[28:31], v[142:145], v[198:201], v[28:31]
	v_mfma_f32_16x16x32_bf16 v[24:27], v[158:161], v[198:201], v[24:27]
	v_mfma_f32_16x16x32_bf16 v[12:15], v[142:145], v[210:213], v[12:15]
	v_mfma_f32_16x16x32_bf16 v[8:11], v[158:161], v[210:213], v[8:11]
	s_setprio 0
	s_setprio 1
	v_mfma_f32_16x16x32_bf16 v[52:55], v[162:165], v[178:181], v[52:55]
	v_mfma_f32_16x16x32_bf16 v[48:51], v[170:173], v[178:181], v[48:51]
	v_mfma_f32_16x16x32_bf16 v[36:39], v[162:165], v[186:189], v[36:39]
	v_mfma_f32_16x16x32_bf16 v[32:35], v[170:173], v[186:189], v[32:35]
	v_mfma_f32_16x16x32_bf16 v[20:23], v[162:165], v[194:197], v[20:23]
	v_mfma_f32_16x16x32_bf16 v[16:19], v[170:173], v[194:197], v[16:19]
	v_mfma_f32_16x16x32_bf16 v[4:7], v[162:165], v[202:205], v[4:7]
	v_mfma_f32_16x16x32_bf16 v[0:3], v[170:173], v[202:205], v[0:3]
	v_mfma_f32_16x16x32_bf16 v[52:55], v[166:169], v[182:185], v[52:55]
	v_mfma_f32_16x16x32_bf16 v[48:51], v[174:177], v[182:185], v[48:51]
	v_mfma_f32_16x16x32_bf16 v[36:39], v[166:169], v[190:193], v[36:39]
	v_mfma_f32_16x16x32_bf16 v[32:35], v[174:177], v[190:193], v[32:35]
	v_mfma_f32_16x16x32_bf16 v[20:23], v[166:169], v[198:201], v[20:23]
	v_mfma_f32_16x16x32_bf16 v[16:19], v[174:177], v[198:201], v[16:19]
	v_mfma_f32_16x16x32_bf16 v[4:7], v[166:169], v[210:213], v[4:7]
	v_mfma_f32_16x16x32_bf16 v[0:3], v[174:177], v[210:213], v[0:3]
	s_setprio 0
	s_barrier
	s_add_i32 s61, s61, 2
	s_add_u32 s56, s56, 0x8000
	s_addc_u32 s57, s57, 0
	s_add_u32 s58, s58, 0x8000
	s_addc_u32 s59, s59, 0
	s_cmp_gt_u32 s61, 13

; #define PG8_STAGE(bufoff, gbase, voff) do { _Pragma("unroll") for (int _i = 0; _i < 2; ++_i) \
;         __builtin_amdgcn_global_load_lds((const unsigned*)((const char*)(gbase) + (voff)[_i]), (PG8_LAS unsigned*)(lds + (bufoff) + ldsw + _i * 8192), 16, 0, 0); } while (0)
; #define PG8_LDA(dst, b, h) do { _Pragma("unroll") for (int m = 0; m < 4; ++m) _Pragma("unroll") for (int k = 0; k < 2; ++k) dst[m][k] = *(const PG8_LAS bf16x8*)(lds + PG8_SA(b, h) + aoff + m * 2048 + k * 1024); } while (0)
; #define PG8_LDB(dst, b, h) do { _Pragma("unroll") for (int n = 0; n < 2; ++n) _Pragma("unroll") for (int k = 0; k < 2; ++k) dst[n][k] = *(const PG8_LAS bf16x8*)(lds + PG8_SB(b, h) + boff + n * 2048 + k * 1024); } while (0)
; #define PG8_SCHED __builtin_amdgcn_sched_barrier(0)
;   __device__ __forceinline__ bool next(int i,AttnUnit&u)const{ if(i>=8)return false; const int s=vcu&7,k=i&3; { const int p_=vcu>>3; u.bh=(p_>>3)*16+(p_&7)*2+(i>>2); } u.qb=(k==0)?s:(k==1)?15-s:(k==2)?16+s:31-s; return true; }
;     __host__ __device__ bool next(int i, Unit& u) const {
;         const long L = (long)i * G + c; if (L >= nwg) return false;
;         int wgid = (int)L; { const int q = nwg / NXCD, r = nwg % NXCD, xcd = wgid % NXCD, off = wgid / NXCD; wgid = (xcd < r ? xcd * (q + 1) : r * (q + 1) + (xcd - r) * q) + off; }
;         const int nig = WGM * nN, gid = wgid / nig, fm = gid * WGM, gsz = (nM - fm) < WGM ? (nM - fm) : WGM;
;         u.pm = fm + ((wgid % nig) % gsz); u.pn = (wgid % nig) / gsz; return true;
; template <class Epi, class Sched, bool ALIGN_EPI = false, bool SP2 = false, bool TA = true>
; __device__ __forceinline__ void gemm_phase(PG8_LAS unsigned char* lds, const Gemm g, const Sched& S, const Epi& E) {
;     ...
;             const char* a1 = cA + (size_t)(t + 1) * kstep;
;             const char* a2 = last ? nA : cA + (size_t)(t + 2) * kstep; const char* b2 = last ? nB : cB + (size_t)(t + 2) * kstepB;
;             const char* a3 = a2 + kstep; const char* b3 = b2 + kstepB;
;             if (last && has_next) S.a_ready(nxt);
;             if constexpr (SP2) {
;             PG8_LDB(B0, 0, 0); PG8_LDB(B1, 0, 1); PG8_SCHED; PG8_LDA(At, 0, 0); PG8_STAGE(PG8_SA(1, 1), a1 + hstep, voffA);
.LBB0_1826:
	s_add_u32 s48, s48, 0x44000
	s_addc_u32 s49, s49, 0
	s_add_u32 s50, s50, 0x8000
	s_addc_u32 s51, s51, 0
	s_mov_b32 s67, -2
	ds_read_b128 v[128:131], v165
	ds_read_b128 v[132:135], v165 offset:1024
	ds_read_b128 v[136:139], v165 offset:2048
	ds_read_b128 v[140:143], v165 offset:3072
	ds_read_b128 v[152:155], v166
	ds_read_b128 v[156:159], v166 offset:1024
	ds_read_b128 v[170:173], v166 offset:2048
	ds_read_b128 v[174:177], v166 offset:3072
	s_add_u32 s68, s48, 0xfffc4000
	s_addc_u32 s69, s49, -1
	s_cmp_eq_u32 s67, 12
	s_cselect_b32 s69, s39, s69
	s_cselect_b32 s68, s46, s68
	s_cselect_b32 s71, s37, s51
	s_cselect_b32 s70, s66, s50
	v_lshl_add_u64 v[206:207], s[48:49], 0, v[144:145]
	s_add_i32 m0, s52, 0xc000
	ds_read_b128 v[178:181], v167
	ds_read_b128 v[182:185], v167 offset:1024
	ds_read_b128 v[186:189], v167 offset:2048
	ds_read_b128 v[190:193], v167 offset:3072
	ds_read_b128 v[194:197], v167 offset:4096
	ds_read_b128 v[198:201], v167 offset:5120
	ds_read_b128 v[202:205], v167 offset:6144
	ds_read_b128 v[210:213], v167 offset:7168
	global_load_lds_dwordx4 v[206:207], off
	v_lshl_add_u64 v[206:207], v[206:207], 0, s[4:5]
	s_add_i32 m0, s52, 0xe000
	s_nop 0
	global_load_lds_dwordx4 v[206:207], off
	s_add_i32 s65, s47, 1
	v_readlane_b32 s40, v255, 4
	s_mul_i32 s2, s65, s62
	s_mul_hi_u32 s3, s65, s40
	s_add_i32 s3, s3, s2
	s_mul_i32 s2, s65, s40
	v_readlane_b32 s41, v255, 5
	s_add_u32 s40, s2, s20
	s_addc_u32 s41, s3, s21
	v_cmp_gt_i64_e32 vcc, s[40:41], v[150:151]
	v_cmp_lt_i64_e64 s[2:3], s[40:41], v[148:149]
	s_cbranch_vccnz .LBB0_1832
	s_ashr_i32 s36, s40, 31
	s_lshr_b32 s36, s36, 29
	s_add_i32 s38, s40, s36
	s_and_b32 s36, s38, -8
	s_sub_i32 s39, s40, s36
	s_cmp_gt_i32 s39, -1
	s_mov_b64 s[36:37], -1
	s_cbranch_scc0 .LBB0_1829
	s_lshl_b32 s40, s39, 6
	s_mov_b64 s[36:37], 0

; #define PG8_STAGE(bufoff, gbase, voff) do { _Pragma("unroll") for (int _i = 0; _i < 2; ++_i) \
;         __builtin_amdgcn_global_load_lds((const unsigned*)((const char*)(gbase) + (voff)[_i]), (PG8_LAS unsigned*)(lds + (bufoff) + ldsw + _i * 8192), 16, 0, 0); } while (0)
; #define PG8_LDA(dst, b, h) do { _Pragma("unroll") for (int m = 0; m < 4; ++m) _Pragma("unroll") for (int k = 0; k < 2; ++k) dst[m][k] = *(const PG8_LAS bf16x8*)(lds + PG8_SA(b, h) + aoff + m * 2048 + k * 1024); } while (0)
; #define PG8_LDB(dst, b, h) do { _Pragma("unroll") for (int n = 0; n < 2; ++n) _Pragma("unroll") for (int k = 0; k < 2; ++k) dst[n][k] = *(const PG8_LAS bf16x8*)(lds + PG8_SB(b, h) + boff + n * 2048 + k * 1024); } while (0)
; #define PG8_WAIT_V(n) asm volatile("s_waitcnt vmcnt(" #n ")" ::: "memory")
; #define PG8_WAIT_L(n) asm volatile("s_waitcnt lgkmcnt(" #n ")" ::: "memory")
; #define PG8_BAR __builtin_amdgcn_s_barrier()
; #define PG8_SCHED __builtin_amdgcn_sched_barrier(0)
; template <class Epi, class Sched, bool ALIGN_EPI = false, bool SP2 = false, bool TA = true>
; __device__ __forceinline__ void gemm_phase(PG8_LAS unsigned char* lds, const Gemm g, const Sched& S, const Epi& E) {
;     ...
;         const char* nA = has_next ? (const char*)g.A + (size_t)nxt.pm * tstep : cA; const char* nB = has_next ? (const char*)g.Bt + (size_t)nxt.pn * tstep : cB;
; #pragma unroll 1
;         for (int t = 0; t < nt; t += 2) {
;             const bool last = (t == nt - 2);
;             const char* a1 = cA + (size_t)(t + 1) * kstep;
;             const char* a2 = last ? nA : cA + (size_t)(t + 2) * kstep; const char* b2 = last ? nB : cB + (size_t)(t + 2) * kstepB;
;             const char* a3 = a2 + kstep; const char* b3 = b2 + kstepB;
;             if (last && has_next) S.a_ready(nxt);
;             if constexpr (SP2) {
;             PG8_LDB(B0, 0, 0); PG8_LDB(B1, 0, 1); PG8_SCHED; PG8_LDA(At, 0, 0); PG8_STAGE(PG8_SA(1, 1), a1 + hstep, voffA);
;             PG8_WAIT_V(8); PG8_WAIT_L(0); PG8_BAR; PG8_MMA(0, 0, At, B0); PG8_MMA(0, 1, At, B1); PG8_BAR; PG8_SCHED;
;             PG8_LDA(At, 0, 1); PG8_STAGE(PG8_SB(0, 0), b2, voffB); PG8_STAGE(PG8_SB(0, 1), b2 + hstep, voffB); PG8_STAGE(PG8_SA(0, 0), a2, voffA);
;             PG8_WAIT_V(8); PG8_WAIT_L(0); PG8_BAR; PG8_MMA(1, 0, At, B0); PG8_MMA(1, 1, At, B1); PG8_BAR; PG8_SCHED;
.LBB0_1832:
	s_ashr_i32 s39, s38, 31
	s_lshl_b64 s[40:41], s[38:39], 19
	s_add_u32 s40, s8, s40
	s_addc_u32 s41, s9, s41
	s_and_b64 s[42:43], s[2:3], exec
	s_cselect_b32 s39, s41, s49
	s_cselect_b32 s46, s40, s48
	s_ashr_i32 s37, s36, 31
	s_lshl_b64 s[42:43], s[36:37], 19
	s_add_u32 s42, s22, s42
	s_addc_u32 s43, s23, s43
	s_and_b64 s[98:99], s[2:3], exec
	s_cselect_b32 s37, s43, s51
	s_cselect_b32 s66, s42, s50
	s_waitcnt vmcnt(8)
	s_waitcnt lgkmcnt(0)
	s_barrier
	s_setprio 1
	s_waitcnt lgkmcnt(0)
	v_mfma_f32_16x16x32_bf16 v[124:127], v[128:131], v[178:181], 0
	v_mfma_f32_16x16x32_bf16 v[120:123], v[136:139], v[178:181], 0
	v_mfma_f32_16x16x32_bf16 v[108:111], v[128:131], v[186:189], 0
	v_mfma_f32_16x16x32_bf16 v[104:107], v[136:139], v[186:189], 0
	v_mfma_f32_16x16x32_bf16 v[92:95], v[128:131], v[194:197], 0
	v_mfma_f32_16x16x32_bf16 v[88:91], v[136:139], v[194:197], 0
	v_mfma_f32_16x16x32_bf16 v[76:79], v[128:131], v[202:205], 0
	v_mfma_f32_16x16x32_bf16 v[72:75], v[136:139], v[202:205], 0
	v_mfma_f32_16x16x32_bf16 v[124:127], v[132:135], v[182:185], v[124:127]
	v_mfma_f32_16x16x32_bf16 v[120:123], v[140:143], v[182:185], v[120:123]
	v_mfma_f32_16x16x32_bf16 v[108:111], v[132:135], v[190:193], v[108:111]
	v_mfma_f32_16x16x32_bf16 v[104:107], v[140:143], v[190:193], v[104:107]
	v_mfma_f32_16x16x32_bf16 v[92:95], v[132:135], v[198:201], v[92:95]
	v_mfma_f32_16x16x32_bf16 v[88:91], v[140:143], v[198:201], v[88:91]
	v_mfma_f32_16x16x32_bf16 v[76:79], v[132:135], v[210:213], v[76:79]
	v_mfma_f32_16x16x32_bf16 v[72:75], v[140:143], v[210:213], v[72:75]
	s_setprio 0
	s_setprio 1
	v_mfma_f32_16x16x32_bf16 v[116:119], v[152:155], v[178:181], 0
	v_mfma_f32_16x16x32_bf16 v[112:115], v[170:173], v[178:181], 0
	v_mfma_f32_16x16x32_bf16 v[100:103], v[152:155], v[186:189], 0
	v_mfma_f32_16x16x32_bf16 v[96:99], v[170:173], v[186:189], 0
	v_mfma_f32_16x16x32_bf16 v[84:87], v[152:155], v[194:197], 0
	v_mfma_f32_16x16x32_bf16 v[80:83], v[170:173], v[194:197], 0
	v_mfma_f32_16x16x32_bf16 v[68:71], v[152:155], v[202:205], 0
	v_mfma_f32_16x16x32_bf16 v[64:67], v[170:173], v[202:205], 0
	v_mfma_f32_16x16x32_bf16 v[116:119], v[156:159], v[182:185], v[116:119]
	v_mfma_f32_16x16x32_bf16 v[112:115], v[174:177], v[182:185], v[112:115]
	v_mfma_f32_16x16x32_bf16 v[100:103], v[156:159], v[190:193], v[100:103]
	v_mfma_f32_16x16x32_bf16 v[96:99], v[174:177], v[190:193], v[96:99]
	v_mfma_f32_16x16x32_bf16 v[84:87], v[156:159], v[198:201], v[84:87]
	v_mfma_f32_16x16x32_bf16 v[80:83], v[174:177], v[198:201], v[80:83]
	v_mfma_f32_16x16x32_bf16 v[68:71], v[156:159], v[210:213], v[68:71]
	v_mfma_f32_16x16x32_bf16 v[64:67], v[174:177], v[210:213], v[64:67]
	s_setprio 0
	s_barrier
	v_lshl_add_u64 v[206:207], s[70:71], 0, v[144:145]
	s_add_i32 s70, s63, s33
	s_mov_b32 m0, s70
	ds_read_b128 v[178:181], v167 offset:16384
	ds_read_b128 v[182:185], v167 offset:17408
	ds_read_b128 v[186:189], v167 offset:18432
	ds_read_b128 v[190:193], v167 offset:19456
	ds_read_b128 v[194:197], v167 offset:20480
	ds_read_b128 v[198:201], v167 offset:21504
	ds_read_b128 v[202:205], v167 offset:22528
	ds_read_b128 v[210:213], v167 offset:23552
	global_load_lds_dwordx4 v[206:207], off
	v_lshl_add_u64 v[214:215], v[206:207], 0, s[4:5]
	s_add_i32 m0, s70, 0x2000
	s_add_i32 s70, s64, s33
	global_load_lds_dwordx4 v[214:215], off
	v_lshl_add_u64 v[214:215], v[206:207], 0, s[6:7]
	s_mov_b32 m0, s70
	s_nop 0
	global_load_lds_dwordx4 v[214:215], off
	v_lshl_add_u64 v[214:215], v[206:207], 0, s[12:13]
	s_add_i32 m0, s70, 0x2000
	s_nop 0
	global_load_lds_dwordx4 v[214:215], off
	v_lshl_add_u64 v[214:215], s[68:69], 0, v[144:145]
	s_mov_b32 m0, s52
	v_lshl_add_u64 v[216:217], v[214:215], 0, s[4:5]
	global_load_lds_dwordx4 v[214:215], off
	s_mov_b32 m0, s53
	s_nop 0
	global_load_lds_dwordx4 v[216:217], off
	s_waitcnt vmcnt(8)
	s_waitcnt lgkmcnt(0)
	s_barrier
	s_setprio 1
	s_waitcnt lgkmcnt(0)
	v_mfma_f32_16x16x32_bf16 v[60:63], v[128:131], v[178:181], 0
	v_mfma_f32_16x16x32_bf16 v[56:59], v[136:139], v[178:181], 0
	v_mfma_f32_16x16x32_bf16 v[44:47], v[128:131], v[186:189], 0
	v_mfma_f32_16x16x32_bf16 v[40:43], v[136:139], v[186:189], 0
	v_mfma_f32_16x16x32_bf16 v[28:31], v[128:131], v[194:197], 0
	v_mfma_f32_16x16x32_bf16 v[24:27], v[136:139], v[194:197], 0
	v_mfma_f32_16x16x32_bf16 v[12:15], v[128:131], v[202:205], 0
	v_mfma_f32_16x16x32_bf16 v[8:11], v[136:139], v[202:205], 0
	v_mfma_f32_16x16x32_bf16 v[60:63], v[132:135], v[182:185], v[60:63]
	v_mfma_f32_16x16x32_bf16 v[56:59], v[140:143], v[182:185], v[56:59]
	v_mfma_f32_16x16x32_bf16 v[44:47], v[132:135], v[190:193], v[44:47]
	v_mfma_f32_16x16x32_bf16 v[40:43], v[140:143], v[190:193], v[40:43]
	v_mfma_f32_16x16x32_bf16 v[28:31], v[132:135], v[198:201], v[28:31]
	v_mfma_f32_16x16x32_bf16 v[24:27], v[140:143], v[198:201], v[24:27]
	v_mfma_f32_16x16x32_bf16 v[12:15], v[132:135], v[210:213], v[12:15]
	v_mfma_f32_16x16x32_bf16 v[8:11], v[140:143], v[210:213], v[8:11]
	s_setprio 0
	s_setprio 1
	v_mfma_f32_16x16x32_bf16 v[52:55], v[152:155], v[178:181], 0
	v_mfma_f32_16x16x32_bf16 v[48:51], v[170:173], v[178:181], 0
	v_mfma_f32_16x16x32_bf16 v[36:39], v[152:155], v[186:189], 0
	v_mfma_f32_16x16x32_bf16 v[32:35], v[170:173], v[186:189], 0
	v_mfma_f32_16x16x32_bf16 v[20:23], v[152:155], v[194:197], 0
	v_mfma_f32_16x16x32_bf16 v[16:19], v[170:173], v[194:197], 0
	v_mfma_f32_16x16x32_bf16 v[4:7], v[152:155], v[202:205], 0
	v_mfma_f32_16x16x32_bf16 v[0:3], v[170:173], v[202:205], 0
	v_mfma_f32_16x16x32_bf16 v[52:55], v[156:159], v[182:185], v[52:55]
	v_mfma_f32_16x16x32_bf16 v[48:51], v[174:177], v[182:185], v[48:51]
	v_mfma_f32_16x16x32_bf16 v[36:39], v[156:159], v[190:193], v[36:39]
	v_mfma_f32_16x16x32_bf16 v[32:35], v[174:177], v[190:193], v[32:35]
	v_mfma_f32_16x16x32_bf16 v[20:23], v[156:159], v[198:201], v[20:23]
	v_mfma_f32_16x16x32_bf16 v[16:19], v[174:177], v[198:201], v[16:19]
	v_mfma_f32_16x16x32_bf16 v[4:7], v[156:159], v[210:213], v[4:7]
	v_mfma_f32_16x16x32_bf16 v[0:3], v[174:177], v[210:213], v[0:3]
	s_setprio 0
	s_barrier
; #define PG8_STAGE(bufoff, gbase, voff) do { _Pragma("unroll") for (int _i = 0; _i < 2; ++_i) \
;         __builtin_amdgcn_global_load_lds((const unsigned*)((const char*)(gbase) + (voff)[_i]), (PG8_LAS unsigned*)(lds + (bufoff) + ldsw + _i * 8192), 16, 0, 0); } while (0)
; #define PG8_LDA(dst, b, h) do { _Pragma("unroll") for (int m = 0; m < 4; ++m) _Pragma("unroll") for (int k = 0; k < 2; ++k) dst[m][k] = *(const PG8_LAS bf16x8*)(lds + PG8_SA(b, h) + aoff + m * 2048 + k * 1024); } while (0)
; #define PG8_LDB(dst, b, h) do { _Pragma("unroll") for (int n = 0; n < 2; ++n) _Pragma("unroll") for (int k = 0; k < 2; ++k) dst[n][k] = *(const PG8_LAS bf16x8*)(lds + PG8_SB(b, h) + boff + n * 2048 + k * 1024); } while (0)
; #define PG8_MMA(ai, bj, At, Bt) do { __builtin_amdgcn_s_setprio(1); _Pragma("unroll") for (int m = 0; m < 4; ++m) _Pragma("unroll") for (int n = 0; n < 2; ++n) _Pragma("unroll") for (int k = 0; k < 2; ++k) \
;         acc[ai][bj][m][n] = __builtin_amdgcn_mfma_f32_16x16x32_bf16(Bt[n][k], At[m][k], acc[ai][bj][m][n], 0, 0, 0); __builtin_amdgcn_s_setprio(0); } while (0)
; #define PG8_WAIT_V(n) asm volatile("s_waitcnt vmcnt(" #n ")" ::: "memory")
; #define PG8_WAIT_L(n) asm volatile("s_waitcnt lgkmcnt(" #n ")" ::: "memory")
; #define PG8_BAR __builtin_amdgcn_s_barrier()
; #define PG8_SCHED __builtin_amdgcn_sched_barrier(0)
; template <class Epi, class Sched, bool ALIGN_EPI = false, bool SP2 = false, bool TA = true>
; __device__ __forceinline__ void gemm_phase(PG8_LAS unsigned char* lds, const Gemm g, const Sched& S, const Epi& E) {
;     ...
;             PG8_LDB(B0, 1, 0); PG8_LDB(B1, 1, 1); PG8_SCHED; PG8_LDA(At, 1, 0); PG8_STAGE(PG8_SA(0, 1), a2 + hstep, voffA);
;             PG8_WAIT_V(8); PG8_WAIT_L(0); PG8_BAR; PG8_MMA(0, 0, At, B0); PG8_MMA(0, 1, At, B1); PG8_BAR; PG8_SCHED;
;             PG8_LDA(At, 1, 1); PG8_STAGE(PG8_SB(1, 0), b3, voffB); PG8_STAGE(PG8_SB(1, 1), b3 + hstep, voffB); PG8_STAGE(PG8_SA(1, 0), a3, voffA);
;             PG8_WAIT_V(8); PG8_WAIT_L(0); PG8_BAR; PG8_MMA(1, 0, At, B0); PG8_MMA(1, 1, At, B1); PG8_BAR; PG8_SCHED;
	s_add_i32 s68, 0, 0x18000
	s_add_i32 s69, 0, 0x1c000
	v_add_u32_e32 v140, s68, v162
	v_add_u32_e32 v146, s69, v162
	ds_read_b128 v[128:131], v140
	ds_read_b128 v[132:135], v140 offset:1024
	ds_read_b128 v[136:139], v140 offset:2048
	ds_read_b128 v[140:143], v140 offset:3072
	ds_read_b128 v[152:155], v146
	ds_read_b128 v[156:159], v146 offset:1024
	ds_read_b128 v[170:173], v146 offset:2048
	ds_read_b128 v[174:177], v146 offset:3072
	s_mov_b32 m0, s54
	v_lshl_add_u64 v[216:217], v[214:215], 0, s[6:7]
	ds_read_b128 v[178:181], v167 offset:32768
	ds_read_b128 v[182:185], v167 offset:33792
	ds_read_b128 v[186:189], v167 offset:34816
	ds_read_b128 v[190:193], v167 offset:35840
	ds_read_b128 v[194:197], v167 offset:36864
	ds_read_b128 v[198:201], v167 offset:37888
	ds_read_b128 v[202:205], v167 offset:38912
	ds_read_b128 v[210:213], v167 offset:39936
	global_load_lds_dwordx4 v[216:217], off
	v_lshl_add_u64 v[216:217], v[214:215], 0, s[12:13]
	s_mov_b32 m0, s55
	s_nop 0
	global_load_lds_dwordx4 v[216:217], off
	s_waitcnt vmcnt(8)
	s_waitcnt lgkmcnt(0)
	s_barrier
	s_setprio 1
	s_waitcnt lgkmcnt(0)
	v_mfma_f32_16x16x32_bf16 v[124:127], v[128:131], v[178:181], v[124:127]
	v_mfma_f32_16x16x32_bf16 v[120:123], v[136:139], v[178:181], v[120:123]
	v_mfma_f32_16x16x32_bf16 v[108:111], v[128:131], v[186:189], v[108:111]
	v_mfma_f32_16x16x32_bf16 v[104:107], v[136:139], v[186:189], v[104:107]
	v_mfma_f32_16x16x32_bf16 v[92:95], v[128:131], v[194:197], v[92:95]
	v_mfma_f32_16x16x32_bf16 v[88:91], v[136:139], v[194:197], v[88:91]
	v_mfma_f32_16x16x32_bf16 v[76:79], v[128:131], v[202:205], v[76:79]
	v_mfma_f32_16x16x32_bf16 v[72:75], v[136:139], v[202:205], v[72:75]
	v_mfma_f32_16x16x32_bf16 v[124:127], v[132:135], v[182:185], v[124:127]
	v_mfma_f32_16x16x32_bf16 v[120:123], v[140:143], v[182:185], v[120:123]
	v_mfma_f32_16x16x32_bf16 v[108:111], v[132:135], v[190:193], v[108:111]
	v_mfma_f32_16x16x32_bf16 v[104:107], v[140:143], v[190:193], v[104:107]
	v_mfma_f32_16x16x32_bf16 v[92:95], v[132:135], v[198:201], v[92:95]
	v_mfma_f32_16x16x32_bf16 v[88:91], v[140:143], v[198:201], v[88:91]
	v_mfma_f32_16x16x32_bf16 v[76:79], v[132:135], v[210:213], v[76:79]
	v_mfma_f32_16x16x32_bf16 v[72:75], v[140:143], v[210:213], v[72:75]
	s_setprio 0
	s_setprio 1
	v_mfma_f32_16x16x32_bf16 v[116:119], v[152:155], v[178:181], v[116:119]
	v_mfma_f32_16x16x32_bf16 v[112:115], v[170:173], v[178:181], v[112:115]
	v_mfma_f32_16x16x32_bf16 v[100:103], v[152:155], v[186:189], v[100:103]
	v_mfma_f32_16x16x32_bf16 v[96:99], v[170:173], v[186:189], v[96:99]
	v_mfma_f32_16x16x32_bf16 v[84:87], v[152:155], v[194:197], v[84:87]
	v_mfma_f32_16x16x32_bf16 v[80:83], v[170:173], v[194:197], v[80:83]
	v_mfma_f32_16x16x32_bf16 v[68:71], v[152:155], v[202:205], v[68:71]
	v_mfma_f32_16x16x32_bf16 v[64:67], v[170:173], v[202:205], v[64:67]
	v_mfma_f32_16x16x32_bf16 v[116:119], v[156:159], v[182:185], v[116:119]
	v_mfma_f32_16x16x32_bf16 v[112:115], v[174:177], v[182:185], v[112:115]
	v_mfma_f32_16x16x32_bf16 v[100:103], v[156:159], v[190:193], v[100:103]
	v_mfma_f32_16x16x32_bf16 v[96:99], v[174:177], v[190:193], v[96:99]
	v_mfma_f32_16x16x32_bf16 v[84:87], v[156:159], v[198:201], v[84:87]
	v_mfma_f32_16x16x32_bf16 v[80:83], v[174:177], v[198:201], v[80:83]
	v_mfma_f32_16x16x32_bf16 v[68:71], v[156:159], v[210:213], v[68:71]
	v_mfma_f32_16x16x32_bf16 v[64:67], v[174:177], v[210:213], v[64:67]
	s_setprio 0
	s_barrier
	s_add_i32 s68, s68, s33
	v_lshl_add_u64 v[216:217], v[206:207], 0, s[18:19]
	s_mov_b32 m0, s68
	ds_read_b128 v[178:181], v167 offset:49152
	ds_read_b128 v[182:185], v167 offset:50176
	ds_read_b128 v[186:189], v167 offset:51200
	ds_read_b128 v[190:193], v167 offset:52224
	ds_read_b128 v[194:197], v167 offset:53248
	ds_read_b128 v[198:201], v167 offset:54272
	ds_read_b128 v[202:205], v167 offset:55296
	ds_read_b128 v[210:213], v167 offset:56320
	global_load_lds_dwordx4 v[216:217], off
	v_lshl_add_u64 v[216:217], v[206:207], 0, s[24:25]
	s_add_i32 m0, s68, 0x2000
	s_add_i32 s68, s69, s33
	global_load_lds_dwordx4 v[216:217], off
	v_lshl_add_u64 v[216:217], v[206:207], 0, s[28:29]
	s_mov_b32 m0, s68
	v_lshl_add_u64 v[206:207], v[206:207], 0, s[30:31]
	global_load_lds_dwordx4 v[216:217], off
	s_add_i32 m0, s68, 0x2000
	s_nop 0
	global_load_lds_dwordx4 v[206:207], off
	v_lshl_add_u64 v[206:207], v[214:215], 0, s[18:19]
	s_mov_b32 m0, s58
	s_nop 0
	global_load_lds_dwordx4 v[206:207], off
	v_lshl_add_u64 v[206:207], v[214:215], 0, s[24:25]
	s_mov_b32 m0, s59
	s_nop 0
	global_load_lds_dwordx4 v[206:207], off
	s_waitcnt vmcnt(8)
	s_waitcnt lgkmcnt(0)
	s_barrier
	s_setprio 1
	s_waitcnt lgkmcnt(0)
	v_mfma_f32_16x16x32_bf16 v[60:63], v[128:131], v[178:181], v[60:63]
	v_mfma_f32_16x16x32_bf16 v[56:59], v[136:139], v[178:181], v[56:59]
	v_mfma_f32_16x16x32_bf16 v[44:47], v[128:131], v[186:189], v[44:47]
	v_mfma_f32_16x16x32_bf16 v[40:43], v[136:139], v[186:189], v[40:43]
	v_mfma_f32_16x16x32_bf16 v[28:31], v[128:131], v[194:197], v[28:31]
	v_mfma_f32_16x16x32_bf16 v[24:27], v[136:139], v[194:197], v[24:27]
	v_mfma_f32_16x16x32_bf16 v[12:15], v[128:131], v[202:205], v[12:15]
	v_mfma_f32_16x16x32_bf16 v[8:11], v[136:139], v[202:205], v[8:11]
	v_mfma_f32_16x16x32_bf16 v[60:63], v[132:135], v[182:185], v[60:63]
	v_mfma_f32_16x16x32_bf16 v[56:59], v[140:143], v[182:185], v[56:59]
	v_mfma_f32_16x16x32_bf16 v[44:47], v[132:135], v[190:193], v[44:47]
	v_mfma_f32_16x16x32_bf16 v[40:43], v[140:143], v[190:193], v[40:43]
	v_mfma_f32_16x16x32_bf16 v[28:31], v[132:135], v[198:201], v[28:31]
	v_mfma_f32_16x16x32_bf16 v[24:27], v[140:143], v[198:201], v[24:27]
	v_mfma_f32_16x16x32_bf16 v[12:15], v[132:135], v[210:213], v[12:15]
	v_mfma_f32_16x16x32_bf16 v[8:11], v[140:143], v[210:213], v[8:11]
	s_setprio 0
	s_setprio 1
	v_mfma_f32_16x16x32_bf16 v[52:55], v[152:155], v[178:181], v[52:55]
	v_mfma_f32_16x16x32_bf16 v[48:51], v[170:173], v[178:181], v[48:51]
	v_mfma_f32_16x16x32_bf16 v[36:39], v[152:155], v[186:189], v[36:39]
	v_mfma_f32_16x16x32_bf16 v[32:35], v[170:173], v[186:189], v[32:35]
	v_mfma_f32_16x16x32_bf16 v[20:23], v[152:155], v[194:197], v[20:23]
	v_mfma_f32_16x16x32_bf16 v[16:19], v[170:173], v[194:197], v[16:19]
	v_mfma_f32_16x16x32_bf16 v[4:7], v[152:155], v[202:205], v[4:7]
	v_mfma_f32_16x16x32_bf16 v[0:3], v[170:173], v[202:205], v[0:3]
	v_mfma_f32_16x16x32_bf16 v[52:55], v[156:159], v[182:185], v[52:55]
	v_mfma_f32_16x16x32_bf16 v[48:51], v[174:177], v[182:185], v[48:51]
	v_mfma_f32_16x16x32_bf16 v[36:39], v[156:159], v[190:193], v[36:39]
	v_mfma_f32_16x16x32_bf16 v[32:35], v[174:177], v[190:193], v[32:35]
	v_mfma_f32_16x16x32_bf16 v[20:23], v[156:159], v[198:201], v[20:23]
	v_mfma_f32_16x16x32_bf16 v[16:19], v[174:177], v[198:201], v[16:19]
	v_mfma_f32_16x16x32_bf16 v[4:7], v[156:159], v[210:213], v[4:7]
	v_mfma_f32_16x16x32_bf16 v[0:3], v[174:177], v[210:213], v[0:3]
	s_setprio 0
	s_barrier
	s_add_i32 s67, s67, 2
	s_add_u32 s48, s48, 0x8000
	s_addc_u32 s49, s49, 0
	s_add_u32 s50, s50, 0x8000
	s_addc_u32 s51, s51, 0
	s_cmp_gt_u32 s67, 13
